# LN GEMM epilogues (FFN_UP LN, QKV, SGU-in): row-statistics loads issued at tile start into spare VGPRs, consumed in the epilogue
# baseline (speedup 1.0000x reference)
; template <class Epi, class Sched, bool ALIGN_EPI = false, bool SP2 = false>
; __device__ __forceinline__ void gemm_phase(PG8_LAS unsigned char* lds, const Gemm g, const Sched& S, const Epi& E) {
;     ...
;         const char* nA = has_next ? (const char*)g.A + (size_t)nxt.pm * tstepA : cA; const char* nB = has_next ? (const char*)g.Bt + (size_t)nxt.pn * tstepB : cB;
;         for (int t = 0; t < nt; t += 2) {
;             const bool last = (t == nt - 2);
;             const char* a1 = cA + (long)(t + 1) * kstepA;
;             const char* a2 = last ? nA : cA + (long)(t + 2) * kstepA; const char* b2 = last ? nB : cB + (long)(t + 2) * kstep;
;     ...
; #pragma unroll
;         for (int a = 0; a < 2; ++a)
; #pragma unroll
;             for (int b = 0; b < 2; ++b)
; #pragma unroll
;                 for (int m = 0; m < 4; ++m)
; #pragma unroll
;                     for (int n = 0; n < 2; ++n) acc[a][b][m][n] = (f32x4){0.f, 0.f, 0.f, 0.f};
;         cur = nxt; cA = nA; cB = nB; ++ui;
.LBB0_431:
	s_ashr_i32 s41, s40, 31
	s_lshl_b64 s[8:9], s[40:41], 19
	s_add_u32 s42, s4, s8
	s_addc_u32 s43, s5, s9
	s_ashr_i32 s37, s36, 31
	s_lshl_b64 s[8:9], s[36:37], 19
	s_add_u32 s44, s15, s8
	v_mov_b32_e32 v127, 0
	s_addc_u32 s45, s16, s9
	s_andn2_b64 vcc, exec, s[28:29]
	v_mov_b32_e32 v126, v127
	v_mov_b32_e32 v125, v127
	v_mov_b32_e32 v124, v127
	v_mov_b32_e32 v123, v127
	v_mov_b32_e32 v122, v127
	v_mov_b32_e32 v121, v127
	v_mov_b32_e32 v120, v127
	v_mov_b32_e32 v111, v127
	v_mov_b32_e32 v110, v127
	v_mov_b32_e32 v109, v127
	v_mov_b32_e32 v108, v127
	v_mov_b32_e32 v107, v127
	v_mov_b32_e32 v106, v127
	v_mov_b32_e32 v105, v127
	v_mov_b32_e32 v104, v127
	v_mov_b32_e32 v95, v127
	v_mov_b32_e32 v94, v127
	v_mov_b32_e32 v93, v127
	v_mov_b32_e32 v92, v127
	v_mov_b32_e32 v91, v127
	v_mov_b32_e32 v90, v127
	v_mov_b32_e32 v89, v127
	v_mov_b32_e32 v88, v127
	v_mov_b32_e32 v79, v127
	s_waitcnt lgkmcnt(0)
	v_mov_b32_e32 v78, v127
	v_mov_b32_e32 v77, v127
	v_mov_b32_e32 v76, v127
	v_mov_b32_e32 v75, v127
	v_mov_b32_e32 v74, v127
	v_mov_b32_e32 v73, v127
	v_mov_b32_e32 v72, v127
	v_mov_b32_e32 v119, v127
	v_mov_b32_e32 v118, v127
	v_mov_b32_e32 v117, v127
	v_mov_b32_e32 v116, v127
	v_mov_b32_e32 v115, v127
	v_mov_b32_e32 v114, v127
	v_mov_b32_e32 v113, v127
	v_mov_b32_e32 v112, v127
	v_mov_b32_e32 v103, v127
	v_mov_b32_e32 v102, v127
	v_mov_b32_e32 v101, v127
	v_mov_b32_e32 v100, v127
	v_mov_b32_e32 v99, v127
	v_mov_b32_e32 v98, v127
	v_mov_b32_e32 v97, v127
	v_mov_b32_e32 v96, v127
	v_mov_b32_e32 v87, v127
	v_mov_b32_e32 v86, v127
	v_mov_b32_e32 v85, v127
	v_mov_b32_e32 v84, v127
	v_mov_b32_e32 v83, v127
	v_mov_b32_e32 v82, v127
	v_mov_b32_e32 v81, v127
	v_mov_b32_e32 v80, v127
	v_mov_b32_e32 v71, v127
	v_mov_b32_e32 v70, v127
	v_mov_b32_e32 v69, v127
	v_mov_b32_e32 v68, v127
	v_mov_b32_e32 v67, v127
	v_mov_b32_e32 v66, v127
	v_mov_b32_e32 v65, v127
	v_mov_b32_e32 v64, v127
	v_mov_b32_e32 v63, v127
	v_mov_b32_e32 v62, v127
	v_mov_b32_e32 v61, v127
	v_mov_b32_e32 v60, v127
	v_mov_b32_e32 v59, v127
	v_mov_b32_e32 v58, v127
	v_mov_b32_e32 v57, v127
	v_mov_b32_e32 v56, v127
	v_mov_b32_e32 v47, v127
	v_mov_b32_e32 v46, v127
	v_mov_b32_e32 v45, v127
	v_mov_b32_e32 v44, v127
	v_mov_b32_e32 v43, v127
	v_mov_b32_e32 v42, v127
	v_mov_b32_e32 v41, v127
	v_mov_b32_e32 v40, v127
	v_mov_b32_e32 v31, v127
	v_mov_b32_e32 v30, v127
	v_mov_b32_e32 v29, v127
	v_mov_b32_e32 v28, v127
	v_mov_b32_e32 v27, v127
	v_mov_b32_e32 v26, v127
	v_mov_b32_e32 v25, v127
	v_mov_b32_e32 v24, v127
	v_mov_b32_e32 v15, v127
	v_mov_b32_e32 v14, v127
	v_mov_b32_e32 v13, v127
	v_mov_b32_e32 v12, v127
	v_mov_b32_e32 v11, v127
	v_mov_b32_e32 v10, v127
	v_mov_b32_e32 v9, v127
	v_mov_b32_e32 v8, v127
	v_mov_b32_e32 v55, v127
	v_mov_b32_e32 v54, v127
	v_mov_b32_e32 v53, v127
	v_mov_b32_e32 v52, v127
	v_mov_b32_e32 v51, v127
	v_mov_b32_e32 v50, v127
	v_mov_b32_e32 v49, v127
	v_mov_b32_e32 v48, v127
	v_mov_b32_e32 v39, v127
	v_mov_b32_e32 v38, v127
	v_mov_b32_e32 v37, v127
	v_mov_b32_e32 v36, v127
	v_mov_b32_e32 v35, v127
	v_mov_b32_e32 v34, v127
	v_mov_b32_e32 v33, v127
	v_mov_b32_e32 v32, v127
	v_mov_b32_e32 v23, v127
	v_mov_b32_e32 v22, v127
	v_mov_b32_e32 v21, v127
	v_mov_b32_e32 v20, v127
	v_mov_b32_e32 v19, v127
	v_mov_b32_e32 v18, v127
	v_mov_b32_e32 v17, v127
	v_mov_b32_e32 v16, v127
	v_mov_b32_e32 v7, v127
	v_mov_b32_e32 v6, v127
	v_mov_b32_e32 v5, v127
	v_mov_b32_e32 v4, v127
	v_mov_b32_e32 v3, v127
	v_mov_b32_e32 v2, v127
	v_mov_b32_e32 v1, v127
	v_mov_b32_e32 v0, v127
	s_cbranch_vccnz .LBB0_434
	s_and_b64 s[8:9], s[38:39], exec
	s_cselect_b32 s8, s43, s51
	s_cselect_b32 s9, s42, s50
	s_cselect_b32 s37, s45, s53
	s_cselect_b32 s41, s44, s52
	s_add_u32 s50, s50, 0x40080
	s_addc_u32 s51, s51, 0
	s_add_u32 s47, s52, 0x100
	v_mov_b32_e32 v0, 0
	s_addc_u32 s67, s53, 0
	s_mov_b32 s52, 0
	v_mov_b32_e32 v1, v0
	v_mov_b32_e32 v2, v0
	v_mov_b32_e32 v3, v0
	v_mov_b32_e32 v4, v0
	v_mov_b32_e32 v5, v0
	v_mov_b32_e32 v6, v0
	v_mov_b32_e32 v7, v0
	v_mov_b32_e32 v16, v0
	v_mov_b32_e32 v17, v0
	v_mov_b32_e32 v18, v0
	v_mov_b32_e32 v19, v0
	v_mov_b32_e32 v20, v0
	v_mov_b32_e32 v21, v0
	v_mov_b32_e32 v22, v0
	v_mov_b32_e32 v23, v0
	v_mov_b32_e32 v32, v0
	v_mov_b32_e32 v33, v0
	v_mov_b32_e32 v34, v0
	v_mov_b32_e32 v35, v0
	v_mov_b32_e32 v36, v0
	v_mov_b32_e32 v37, v0
	v_mov_b32_e32 v38, v0
	v_mov_b32_e32 v39, v0
	v_mov_b32_e32 v48, v0
	v_mov_b32_e32 v49, v0
	v_mov_b32_e32 v50, v0
	v_mov_b32_e32 v51, v0
	v_mov_b32_e32 v52, v0
	v_mov_b32_e32 v53, v0
	v_mov_b32_e32 v54, v0
	v_mov_b32_e32 v55, v0
	v_mov_b32_e32 v8, v0
	v_mov_b32_e32 v9, v0
	v_mov_b32_e32 v10, v0
	v_mov_b32_e32 v11, v0
	v_mov_b32_e32 v12, v0
	v_mov_b32_e32 v13, v0
	v_mov_b32_e32 v14, v0
	v_mov_b32_e32 v15, v0
	v_mov_b32_e32 v24, v0
	v_mov_b32_e32 v25, v0
	v_mov_b32_e32 v26, v0
	v_mov_b32_e32 v27, v0
	v_mov_b32_e32 v28, v0
	v_mov_b32_e32 v29, v0
	v_mov_b32_e32 v30, v0
	v_mov_b32_e32 v31, v0
	v_mov_b32_e32 v40, v0
	v_mov_b32_e32 v41, v0
	v_mov_b32_e32 v42, v0
	v_mov_b32_e32 v43, v0
	v_mov_b32_e32 v44, v0
	v_mov_b32_e32 v45, v0
	v_mov_b32_e32 v46, v0
	v_mov_b32_e32 v47, v0
	v_mov_b32_e32 v56, v0
	v_mov_b32_e32 v57, v0
	v_mov_b32_e32 v58, v0
	v_mov_b32_e32 v59, v0
	v_mov_b32_e32 v60, v0
	v_mov_b32_e32 v61, v0
	v_mov_b32_e32 v62, v0
	v_mov_b32_e32 v63, v0
	v_mov_b32_e32 v64, v0
	v_mov_b32_e32 v65, v0
	v_mov_b32_e32 v66, v0
	v_mov_b32_e32 v67, v0
	v_mov_b32_e32 v68, v0
	v_mov_b32_e32 v69, v0
	v_mov_b32_e32 v70, v0
	v_mov_b32_e32 v71, v0
	v_mov_b32_e32 v80, v0
	v_mov_b32_e32 v81, v0
	v_mov_b32_e32 v82, v0
	v_mov_b32_e32 v83, v0
	v_mov_b32_e32 v84, v0
	v_mov_b32_e32 v85, v0
	v_mov_b32_e32 v86, v0
	v_mov_b32_e32 v87, v0
	v_mov_b32_e32 v96, v0
	v_mov_b32_e32 v97, v0
	v_mov_b32_e32 v98, v0
	v_mov_b32_e32 v99, v0
	v_mov_b32_e32 v100, v0
	v_mov_b32_e32 v101, v0
	v_mov_b32_e32 v102, v0
	v_mov_b32_e32 v103, v0
	v_mov_b32_e32 v112, v0
	v_mov_b32_e32 v113, v0
	v_mov_b32_e32 v114, v0
	v_mov_b32_e32 v115, v0
	v_mov_b32_e32 v116, v0
	v_mov_b32_e32 v117, v0
	v_mov_b32_e32 v118, v0
	v_mov_b32_e32 v119, v0
	v_mov_b32_e32 v72, v0
	v_mov_b32_e32 v73, v0
	v_mov_b32_e32 v74, v0
	v_mov_b32_e32 v75, v0
	v_mov_b32_e32 v76, v0
	v_mov_b32_e32 v77, v0
	v_mov_b32_e32 v78, v0
	v_mov_b32_e32 v79, v0
	v_mov_b32_e32 v88, v0
	v_mov_b32_e32 v89, v0
	v_mov_b32_e32 v90, v0
	v_mov_b32_e32 v91, v0
	v_mov_b32_e32 v92, v0
	v_mov_b32_e32 v93, v0
	v_mov_b32_e32 v94, v0
	v_mov_b32_e32 v95, v0
	v_mov_b32_e32 v104, v0
	v_mov_b32_e32 v105, v0
	v_mov_b32_e32 v106, v0
	v_mov_b32_e32 v107, v0
	v_mov_b32_e32 v108, v0
	v_mov_b32_e32 v109, v0
	v_mov_b32_e32 v110, v0
	v_mov_b32_e32 v111, v0
	v_mov_b32_e32 v120, v0
	v_mov_b32_e32 v121, v0
	v_mov_b32_e32 v122, v0
	v_mov_b32_e32 v123, v0
	v_mov_b32_e32 v124, v0
	v_mov_b32_e32 v125, v0
	v_mov_b32_e32 v126, v0
	v_mov_b32_e32 v127, v0
	v_readfirstlane_b32 s98, v254
	s_lshl_b32 s99, s46, 8
	s_nop 0
	s_cmpk_lt_u32 s98, 0x100
	s_cbranch_scc0 .Lrs0_nopre
; #define PG8_STAGE(bufoff, gbase, voff) do { _Pragma("unroll") for (int _i = 0; _i < 2; ++_i) \
;         __builtin_amdgcn_global_load_lds((const unsigned*)((const char*)(gbase) + (voff)[_i]), (PG8_LAS unsigned*)(lds + (bufoff) + ldsw + _i * 8192), 16, 0, 0); } while (0)
; #define PG8_LDA(dst, b, h) do { _Pragma("unroll") for (int m = 0; m < 4; ++m) _Pragma("unroll") for (int k = 0; k < 2; ++k) dst[m][k] = *(const PG8_LAS bf16x8*)(lds + PG8_SA(b, h) + aoff + m * 2048 + k * 1024); } while (0)
; #define PG8_WAIT_V(n) asm volatile("s_waitcnt vmcnt(" #n ")" ::: "memory")
; #define PG8_WAIT_L(n) asm volatile("s_waitcnt lgkmcnt(" #n ")" ::: "memory")
; __device__ __forceinline__ void load_row_stats(const float* sp, int row0, RowStats& r) {
; #pragma unroll
;     for (int ai = 0; ai < 2; ++ai) { asm volatile("" ::: "memory");
; #pragma unroll
;         for (int m = 0; m < 4; ++m) { const float* p = sp + (size_t)(row0 + ai * HALF + m * 16) * 8; const f32x4 a = *(const f32x4*)p, b = *(const f32x4*)(p + 4);
;             const float s1 = (a[0] + a[2]) + (b[0] + b[2]), s2 = (a[1] + a[3]) + (b[1] + b[3]); const float mu = s1 * (1.f / 1024.f); const float var = s2 * (1.f / 1024.f) - mu * mu;
;             r.mu[ai][m] = mu; r.rs[ai][m] = __builtin_amdgcn_rsqf(__builtin_fmaxf(var, 0.f) + 1e-5f); } }
; template <class Epi, class Sched, bool ALIGN_EPI = false, bool SP2 = false>
; __device__ __forceinline__ void gemm_phase(PG8_LAS unsigned char* lds, const Gemm g, const Sched& S, const Epi& E) {
;     ...
;             const char* a1 = cA + (long)(t + 1) * kstepA;
;             const char* a2 = last ? nA : cA + (long)(t + 2) * kstepA; const char* b2 = last ? nB : cB + (long)(t + 2) * kstep;
;             const char* a3 = a2 + kstepA; const char* b3 = b2 + kstep;
;             if (last && has_next) S.a_ready(nxt);
;             if constexpr (SP2) {
;             PG8_LDB(B0, 0, 0); PG8_LDB(B1, 0, 1); PG8_SCHED; PG8_LDA(At, 0, 0); PG8_STAGE(PG8_SA(1, 1), a1 + hstepA, voffA);
;             PG8_WAIT_V(8); PG8_WAIT_L(0); PG8_BAR; PG8_MMA(0, 0, At, B0); PG8_MMA(0, 1, At, B1); PG8_BAR; PG8_SCHED;
;             PG8_LDA(At, 0, 1); PG8_STAGE(PG8_SB(0, 0), b2, voffB); PG8_STAGE(PG8_SB(0, 1), b2 + hstepB, voffB); PG8_STAGE(PG8_SA(0, 0), a2, voffA);
;             PG8_WAIT_V(8); PG8_WAIT_L(0); PG8_BAR; PG8_MMA(1, 0, At, B0); PG8_MMA(1, 1, At, B1); PG8_BAR; PG8_SCHED;
	v_add_u32_e32 v244, s99, v254
	v_mov_b32_e32 v245, 0
	v_lshlrev_b64 v[244:245], 5, v[244:245]
	v_lshl_add_u64 v[244:245], s[12:13], 0, v[244:245]
	global_load_dwordx4 v[246:249], v[244:245], off offset:16
	global_load_dwordx4 v[250:253], v[244:245], off
.Lrs0_nopre:
.LBB0_433:
	ds_read_b128 v[128:131], v199
	ds_read_b128 v[132:135], v199 offset:1024
	ds_read_b128 v[136:139], v199 offset:2048
	ds_read_b128 v[140:143], v199 offset:3072
	ds_read_b128 v[144:147], v205
	ds_read_b128 v[148:151], v205 offset:1024
	ds_read_b128 v[152:155], v205 offset:2048
	ds_read_b128 v[156:159], v205 offset:3072
	s_add_i32 s68, s52, 2
	s_add_u32 s53, s50, 0xfffc0080
	s_addc_u32 s54, s51, -1
	s_cmp_eq_u32 s61, s52
	s_cselect_b32 s52, s41, s47
	s_cselect_b32 s55, s8, s54
	s_cselect_b32 s54, s9, s53
	s_cselect_b32 s53, s37, s67
	v_lshl_add_u64 v[196:197], s[50:51], 0, v[170:171]
	s_add_i32 m0, s18, 0xc000
	ds_read_b128 v[178:181], v213
	ds_read_b128 v[184:187], v213 offset:1024
	ds_read_b128 v[190:193], v213 offset:2048
	ds_read_b128 v[200:203], v213 offset:3072
	ds_read_b128 v[206:209], v213 offset:4096
	ds_read_b128 v[214:217], v213 offset:5120
	ds_read_b128 v[220:223], v213 offset:6144
	ds_read_b128 v[226:229], v213 offset:7168
	global_load_lds_dwordx4 v[196:197], off
	v_lshl_add_u64 v[196:197], s[50:51], 0, v[172:173]
	s_add_i32 m0, s18, 0xe000
	s_nop 0
	global_load_lds_dwordx4 v[196:197], off
	s_waitcnt vmcnt(8)
	s_waitcnt lgkmcnt(0)
	s_barrier
	s_setprio 1
	s_waitcnt lgkmcnt(0)
	v_mfma_f32_16x16x32_bf16 v[124:127], v[128:131], v[178:181], v[124:127]
	v_mfma_f32_16x16x32_bf16 v[120:123], v[136:139], v[178:181], v[120:123]
	v_mfma_f32_16x16x32_bf16 v[108:111], v[128:131], v[190:193], v[108:111]
	v_mfma_f32_16x16x32_bf16 v[104:107], v[136:139], v[190:193], v[104:107]
	v_mfma_f32_16x16x32_bf16 v[92:95], v[128:131], v[206:209], v[92:95]
	v_mfma_f32_16x16x32_bf16 v[88:91], v[136:139], v[206:209], v[88:91]
	v_mfma_f32_16x16x32_bf16 v[76:79], v[128:131], v[220:223], v[76:79]
	v_mfma_f32_16x16x32_bf16 v[72:75], v[136:139], v[220:223], v[72:75]
	v_mfma_f32_16x16x32_bf16 v[124:127], v[132:135], v[184:187], v[124:127]
	v_mfma_f32_16x16x32_bf16 v[120:123], v[140:143], v[184:187], v[120:123]
	v_mfma_f32_16x16x32_bf16 v[108:111], v[132:135], v[200:203], v[108:111]
	v_mfma_f32_16x16x32_bf16 v[104:107], v[140:143], v[200:203], v[104:107]
	v_mfma_f32_16x16x32_bf16 v[92:95], v[132:135], v[214:217], v[92:95]
	v_mfma_f32_16x16x32_bf16 v[88:91], v[140:143], v[214:217], v[88:91]
	v_mfma_f32_16x16x32_bf16 v[76:79], v[132:135], v[226:229], v[76:79]
	v_mfma_f32_16x16x32_bf16 v[72:75], v[140:143], v[226:229], v[72:75]
	s_setprio 0
	s_setprio 1
	v_mfma_f32_16x16x32_bf16 v[116:119], v[144:147], v[178:181], v[116:119]
	v_mfma_f32_16x16x32_bf16 v[112:115], v[152:155], v[178:181], v[112:115]
	v_mfma_f32_16x16x32_bf16 v[100:103], v[144:147], v[190:193], v[100:103]
	v_mfma_f32_16x16x32_bf16 v[96:99], v[152:155], v[190:193], v[96:99]
	v_mfma_f32_16x16x32_bf16 v[84:87], v[144:147], v[206:209], v[84:87]
	v_mfma_f32_16x16x32_bf16 v[80:83], v[152:155], v[206:209], v[80:83]
	v_mfma_f32_16x16x32_bf16 v[68:71], v[144:147], v[220:223], v[68:71]
	v_mfma_f32_16x16x32_bf16 v[64:67], v[152:155], v[220:223], v[64:67]
	v_mfma_f32_16x16x32_bf16 v[116:119], v[148:151], v[184:187], v[116:119]
	v_mfma_f32_16x16x32_bf16 v[112:115], v[156:159], v[184:187], v[112:115]
	v_mfma_f32_16x16x32_bf16 v[100:103], v[148:151], v[200:203], v[100:103]
	v_mfma_f32_16x16x32_bf16 v[96:99], v[156:159], v[200:203], v[96:99]
	v_mfma_f32_16x16x32_bf16 v[84:87], v[148:151], v[214:217], v[84:87]
	v_mfma_f32_16x16x32_bf16 v[80:83], v[156:159], v[214:217], v[80:83]
	v_mfma_f32_16x16x32_bf16 v[68:71], v[148:151], v[226:229], v[68:71]
	v_mfma_f32_16x16x32_bf16 v[64:67], v[156:159], v[226:229], v[64:67]
	s_setprio 0
	s_barrier
	s_add_i32 s69, s65, s17
	v_lshl_add_u64 v[196:197], s[52:53], 0, v[162:163]
	s_mov_b32 m0, s69
	ds_read_b128 v[178:181], v213 offset:16384
	ds_read_b128 v[184:187], v213 offset:17408
	ds_read_b128 v[190:193], v213 offset:18432
	ds_read_b128 v[200:203], v213 offset:19456
	ds_read_b128 v[206:209], v213 offset:20480
	ds_read_b128 v[214:217], v213 offset:21504
	ds_read_b128 v[220:223], v213 offset:22528
	ds_read_b128 v[226:229], v213 offset:23552
	global_load_lds_dwordx4 v[196:197], off
	s_add_i32 m0, s69, 0x2000
	s_add_u32 s70, s52, 0x40000
	v_lshl_add_u64 v[210:211], s[52:53], 0, v[166:167]
	s_addc_u32 s71, s53, 0
	s_add_i32 s69, s66, s17
	global_load_lds_dwordx4 v[210:211], off
	v_lshl_add_u64 v[230:231], s[70:71], 0, v[162:163]
	s_mov_b32 m0, s69
	v_lshl_add_u64 v[232:233], s[54:55], 0, v[164:165]
	global_load_lds_dwordx4 v[230:231], off
	v_lshl_add_u64 v[230:231], s[70:71], 0, v[166:167]
	s_add_i32 m0, s69, 0x2000
	s_nop 0
	global_load_lds_dwordx4 v[230:231], off
	v_lshl_add_u64 v[230:231], s[54:55], 0, v[160:161]
	s_mov_b32 m0, s18
	s_nop 0
	global_load_lds_dwordx4 v[230:231], off
	s_mov_b32 m0, s19
	s_nop 0
	global_load_lds_dwordx4 v[232:233], off
	s_waitcnt vmcnt(8)
	s_waitcnt lgkmcnt(0)
	s_barrier
; #define PG8_STAGE(bufoff, gbase, voff) do { _Pragma("unroll") for (int _i = 0; _i < 2; ++_i) \
;         __builtin_amdgcn_global_load_lds((const unsigned*)((const char*)(gbase) + (voff)[_i]), (PG8_LAS unsigned*)(lds + (bufoff) + ldsw + _i * 8192), 16, 0, 0); } while (0)
; #define PG8_LDA(dst, b, h) do { _Pragma("unroll") for (int m = 0; m < 4; ++m) _Pragma("unroll") for (int k = 0; k < 2; ++k) dst[m][k] = *(const PG8_LAS bf16x8*)(lds + PG8_SA(b, h) + aoff + m * 2048 + k * 1024); } while (0)
; #define PG8_LDB(dst, b, h) do { _Pragma("unroll") for (int n = 0; n < 2; ++n) _Pragma("unroll") for (int k = 0; k < 2; ++k) dst[n][k] = *(const PG8_LAS bf16x8*)(lds + PG8_SB(b, h) + boff + n * 2048 + k * 1024); } while (0)
; #define PG8_MMA(ai, bj, At, Bt) do { __builtin_amdgcn_s_setprio(1); _Pragma("unroll") for (int m = 0; m < 4; ++m) _Pragma("unroll") for (int n = 0; n < 2; ++n) _Pragma("unroll") for (int k = 0; k < 2; ++k) \
;         acc[ai][bj][m][n] = __builtin_amdgcn_mfma_f32_16x16x32_bf16(Bt[n][k], At[m][k], acc[ai][bj][m][n], 0, 0, 0); __builtin_amdgcn_s_setprio(0); } while (0)
; #define PG8_WAIT_V(n) asm volatile("s_waitcnt vmcnt(" #n ")" ::: "memory")
; #define PG8_WAIT_L(n) asm volatile("s_waitcnt lgkmcnt(" #n ")" ::: "memory")
; #define PG8_BAR __builtin_amdgcn_s_barrier()
; #define PG8_SCHED __builtin_amdgcn_sched_barrier(0)
; template <class Epi, class Sched, bool ALIGN_EPI = false, bool SP2 = false>
; __device__ __forceinline__ void gemm_phase(PG8_LAS unsigned char* lds, const Gemm g, const Sched& S, const Epi& E) {
;     ...
;             PG8_WAIT_V(8); PG8_WAIT_L(0); PG8_BAR; PG8_MMA(1, 0, At, B0); PG8_MMA(1, 1, At, B1); PG8_BAR; PG8_SCHED;
;             PG8_LDB(B0, 1, 0); PG8_LDB(B1, 1, 1); PG8_SCHED; PG8_LDA(At, 1, 0); PG8_STAGE(PG8_SA(0, 1), a2 + hstepA, voffA);
;             PG8_WAIT_V(8); PG8_WAIT_L(0); PG8_BAR; PG8_MMA(0, 0, At, B0); PG8_MMA(0, 1, At, B1); PG8_BAR; PG8_SCHED;
;             PG8_LDA(At, 1, 1); PG8_STAGE(PG8_SB(1, 0), b3, voffB); PG8_STAGE(PG8_SB(1, 1), b3 + hstepB, voffB); PG8_STAGE(PG8_SA(1, 0), a3, voffA);
	s_setprio 1
	s_waitcnt lgkmcnt(0)
	v_mfma_f32_16x16x32_bf16 v[60:63], v[128:131], v[178:181], v[60:63]
	v_mfma_f32_16x16x32_bf16 v[56:59], v[136:139], v[178:181], v[56:59]
	v_mfma_f32_16x16x32_bf16 v[44:47], v[128:131], v[190:193], v[44:47]
	v_mfma_f32_16x16x32_bf16 v[40:43], v[136:139], v[190:193], v[40:43]
	v_mfma_f32_16x16x32_bf16 v[28:31], v[128:131], v[206:209], v[28:31]
	v_mfma_f32_16x16x32_bf16 v[24:27], v[136:139], v[206:209], v[24:27]
	v_mfma_f32_16x16x32_bf16 v[12:15], v[128:131], v[220:223], v[12:15]
	v_mfma_f32_16x16x32_bf16 v[8:11], v[136:139], v[220:223], v[8:11]
	v_mfma_f32_16x16x32_bf16 v[60:63], v[132:135], v[184:187], v[60:63]
	v_mfma_f32_16x16x32_bf16 v[56:59], v[140:143], v[184:187], v[56:59]
	v_mfma_f32_16x16x32_bf16 v[44:47], v[132:135], v[200:203], v[44:47]
	v_mfma_f32_16x16x32_bf16 v[40:43], v[140:143], v[200:203], v[40:43]
	v_mfma_f32_16x16x32_bf16 v[28:31], v[132:135], v[214:217], v[28:31]
	v_mfma_f32_16x16x32_bf16 v[24:27], v[140:143], v[214:217], v[24:27]
	v_mfma_f32_16x16x32_bf16 v[12:15], v[132:135], v[226:229], v[12:15]
	v_mfma_f32_16x16x32_bf16 v[8:11], v[140:143], v[226:229], v[8:11]
	s_setprio 0
	s_setprio 1
	v_mfma_f32_16x16x32_bf16 v[52:55], v[144:147], v[178:181], v[52:55]
	v_mfma_f32_16x16x32_bf16 v[48:51], v[152:155], v[178:181], v[48:51]
	v_mfma_f32_16x16x32_bf16 v[36:39], v[144:147], v[190:193], v[36:39]
	v_mfma_f32_16x16x32_bf16 v[32:35], v[152:155], v[190:193], v[32:35]
	v_mfma_f32_16x16x32_bf16 v[20:23], v[144:147], v[206:209], v[20:23]
	v_mfma_f32_16x16x32_bf16 v[16:19], v[152:155], v[206:209], v[16:19]
	v_mfma_f32_16x16x32_bf16 v[4:7], v[144:147], v[220:223], v[4:7]
	v_mfma_f32_16x16x32_bf16 v[0:3], v[152:155], v[220:223], v[0:3]
	v_mfma_f32_16x16x32_bf16 v[52:55], v[148:151], v[184:187], v[52:55]
	v_mfma_f32_16x16x32_bf16 v[48:51], v[156:159], v[184:187], v[48:51]
	v_mfma_f32_16x16x32_bf16 v[36:39], v[148:151], v[200:203], v[36:39]
	v_mfma_f32_16x16x32_bf16 v[32:35], v[156:159], v[200:203], v[32:35]
	v_mfma_f32_16x16x32_bf16 v[20:23], v[148:151], v[214:217], v[20:23]
	v_mfma_f32_16x16x32_bf16 v[16:19], v[156:159], v[214:217], v[16:19]
	v_mfma_f32_16x16x32_bf16 v[4:7], v[148:151], v[226:229], v[4:7]
	v_mfma_f32_16x16x32_bf16 v[0:3], v[156:159], v[226:229], v[0:3]
	s_setprio 0
	s_barrier
	s_add_i32 s69, 0, 0x18000
	s_add_i32 s70, 0, 0x1c000
	v_add_u32_e32 v140, s69, v195
	v_add_u32_e32 v156, s70, v195
	ds_read_b128 v[128:131], v140
	ds_read_b128 v[132:135], v140 offset:1024
	ds_read_b128 v[136:139], v140 offset:2048
	ds_read_b128 v[140:143], v140 offset:3072
	ds_read_b128 v[144:147], v156
	ds_read_b128 v[148:151], v156 offset:1024
	ds_read_b128 v[152:155], v156 offset:2048
	ds_read_b128 v[156:159], v156 offset:3072
	s_add_u32 s54, s54, 0x40000
	s_addc_u32 s55, s55, 0
	s_mov_b32 m0, s20
	v_lshl_add_u64 v[234:235], s[54:55], 0, v[160:161]
	ds_read_b128 v[178:181], v213 offset:32768
	ds_read_b128 v[184:187], v213 offset:33792
	ds_read_b128 v[190:193], v213 offset:34816
	ds_read_b128 v[200:203], v213 offset:35840
	ds_read_b128 v[206:209], v213 offset:36864
	ds_read_b128 v[214:217], v213 offset:37888
	ds_read_b128 v[220:223], v213 offset:38912
	ds_read_b128 v[226:229], v213 offset:39936
	global_load_lds_dwordx4 v[234:235], off
	v_lshl_add_u64 v[234:235], s[54:55], 0, v[164:165]
	s_mov_b32 m0, s21
	s_nop 0
	global_load_lds_dwordx4 v[234:235], off
	s_waitcnt vmcnt(8)
	s_waitcnt lgkmcnt(0)
	s_barrier
	s_setprio 1
	s_waitcnt lgkmcnt(0)
	v_mfma_f32_16x16x32_bf16 v[124:127], v[128:131], v[178:181], v[124:127]
	v_mfma_f32_16x16x32_bf16 v[120:123], v[136:139], v[178:181], v[120:123]
	v_mfma_f32_16x16x32_bf16 v[108:111], v[128:131], v[190:193], v[108:111]
	v_mfma_f32_16x16x32_bf16 v[104:107], v[136:139], v[190:193], v[104:107]
	v_mfma_f32_16x16x32_bf16 v[92:95], v[128:131], v[206:209], v[92:95]
	v_mfma_f32_16x16x32_bf16 v[88:91], v[136:139], v[206:209], v[88:91]
	v_mfma_f32_16x16x32_bf16 v[76:79], v[128:131], v[220:223], v[76:79]
	v_mfma_f32_16x16x32_bf16 v[72:75], v[136:139], v[220:223], v[72:75]
	v_mfma_f32_16x16x32_bf16 v[124:127], v[132:135], v[184:187], v[124:127]
	v_mfma_f32_16x16x32_bf16 v[120:123], v[140:143], v[184:187], v[120:123]
	v_mfma_f32_16x16x32_bf16 v[108:111], v[132:135], v[200:203], v[108:111]
	v_mfma_f32_16x16x32_bf16 v[104:107], v[140:143], v[200:203], v[104:107]
	v_mfma_f32_16x16x32_bf16 v[92:95], v[132:135], v[214:217], v[92:95]
	v_mfma_f32_16x16x32_bf16 v[88:91], v[140:143], v[214:217], v[88:91]
	v_mfma_f32_16x16x32_bf16 v[76:79], v[132:135], v[226:229], v[76:79]
	v_mfma_f32_16x16x32_bf16 v[72:75], v[140:143], v[226:229], v[72:75]
	s_setprio 0
	s_setprio 1
	v_mfma_f32_16x16x32_bf16 v[116:119], v[144:147], v[178:181], v[116:119]
	v_mfma_f32_16x16x32_bf16 v[112:115], v[152:155], v[178:181], v[112:115]
	v_mfma_f32_16x16x32_bf16 v[100:103], v[144:147], v[190:193], v[100:103]
	v_mfma_f32_16x16x32_bf16 v[96:99], v[152:155], v[190:193], v[96:99]
	v_mfma_f32_16x16x32_bf16 v[84:87], v[144:147], v[206:209], v[84:87]
	v_mfma_f32_16x16x32_bf16 v[80:83], v[152:155], v[206:209], v[80:83]
	v_mfma_f32_16x16x32_bf16 v[68:71], v[144:147], v[220:223], v[68:71]
	v_mfma_f32_16x16x32_bf16 v[64:67], v[152:155], v[220:223], v[64:67]
	v_mfma_f32_16x16x32_bf16 v[116:119], v[148:151], v[184:187], v[116:119]
	v_mfma_f32_16x16x32_bf16 v[112:115], v[156:159], v[184:187], v[112:115]
	v_mfma_f32_16x16x32_bf16 v[100:103], v[148:151], v[200:203], v[100:103]
	v_mfma_f32_16x16x32_bf16 v[96:99], v[156:159], v[200:203], v[96:99]
	v_mfma_f32_16x16x32_bf16 v[84:87], v[148:151], v[214:217], v[84:87]
	v_mfma_f32_16x16x32_bf16 v[80:83], v[156:159], v[214:217], v[80:83]
	v_mfma_f32_16x16x32_bf16 v[68:71], v[148:151], v[226:229], v[68:71]
	v_mfma_f32_16x16x32_bf16 v[64:67], v[156:159], v[226:229], v[64:67]
	s_setprio 0
	s_barrier
; #define PG8_STAGE(bufoff, gbase, voff) do { _Pragma("unroll") for (int _i = 0; _i < 2; ++_i) \
;         __builtin_amdgcn_global_load_lds((const unsigned*)((const char*)(gbase) + (voff)[_i]), (PG8_LAS unsigned*)(lds + (bufoff) + ldsw + _i * 8192), 16, 0, 0); } while (0)
; #define PG8_LDA(dst, b, h) do { _Pragma("unroll") for (int m = 0; m < 4; ++m) _Pragma("unroll") for (int k = 0; k < 2; ++k) dst[m][k] = *(const PG8_LAS bf16x8*)(lds + PG8_SA(b, h) + aoff + m * 2048 + k * 1024); } while (0)
; #define PG8_MMA(ai, bj, At, Bt) do { __builtin_amdgcn_s_setprio(1); _Pragma("unroll") for (int m = 0; m < 4; ++m) _Pragma("unroll") for (int n = 0; n < 2; ++n) _Pragma("unroll") for (int k = 0; k < 2; ++k) \
;         acc[ai][bj][m][n] = __builtin_amdgcn_mfma_f32_16x16x32_bf16(Bt[n][k], At[m][k], acc[ai][bj][m][n], 0, 0, 0); __builtin_amdgcn_s_setprio(0); } while (0)
; #define PG8_WAIT_V(n) asm volatile("s_waitcnt vmcnt(" #n ")" ::: "memory")
; #define PG8_WAIT_L(n) asm volatile("s_waitcnt lgkmcnt(" #n ")" ::: "memory")
; #define PG8_BAR __builtin_amdgcn_s_barrier()
; #define PG8_SCHED __builtin_amdgcn_sched_barrier(0)
; template <class Epi, class Sched, bool ALIGN_EPI = false, bool SP2 = false>
; __device__ __forceinline__ void gemm_phase(PG8_LAS unsigned char* lds, const Gemm g, const Sched& S, const Epi& E) {
;     ...
;         for (int t = 0; t < nt; t += 2) {
;             const bool last = (t == nt - 2);
;             const char* a1 = cA + (long)(t + 1) * kstepA;
;             const char* a2 = last ? nA : cA + (long)(t + 2) * kstepA; const char* b2 = last ? nB : cB + (long)(t + 2) * kstep;
;     ...
;             PG8_LDA(At, 1, 1); PG8_STAGE(PG8_SB(1, 0), b3, voffB); PG8_STAGE(PG8_SB(1, 1), b3 + hstepB, voffB); PG8_STAGE(PG8_SA(1, 0), a3, voffA);
;             PG8_WAIT_V(8); PG8_WAIT_L(0); PG8_BAR; PG8_MMA(1, 0, At, B0); PG8_MMA(1, 1, At, B1); PG8_BAR; PG8_SCHED;
	s_add_i32 s54, s69, s17
	v_lshl_add_u64 v[196:197], v[196:197], 0, s[26:27]
	s_mov_b32 m0, s54
	ds_read_b128 v[178:181], v213 offset:49152
	ds_read_b128 v[184:187], v213 offset:50176
	ds_read_b128 v[190:193], v213 offset:51200
	ds_read_b128 v[200:203], v213 offset:52224
	ds_read_b128 v[206:209], v213 offset:53248
	ds_read_b128 v[214:217], v213 offset:54272
	ds_read_b128 v[220:223], v213 offset:55296
	ds_read_b128 v[226:229], v213 offset:56320
	global_load_lds_dwordx4 v[196:197], off
	s_add_i32 m0, s54, 0x2000
	s_add_u32 s52, s52, 0x40080
	v_lshl_add_u64 v[196:197], v[210:211], 0, s[26:27]
	s_addc_u32 s53, s53, 0
	s_add_i32 s54, s70, s17
	global_load_lds_dwordx4 v[196:197], off
	v_lshl_add_u64 v[196:197], s[52:53], 0, v[162:163]
	s_mov_b32 m0, s54
	s_nop 0
	global_load_lds_dwordx4 v[196:197], off
	v_lshl_add_u64 v[196:197], s[52:53], 0, v[166:167]
	s_add_i32 m0, s54, 0x2000
	s_nop 0
	global_load_lds_dwordx4 v[196:197], off
	v_lshl_add_u64 v[196:197], v[230:231], 0, s[26:27]
	s_mov_b32 m0, s59
	s_nop 0
	global_load_lds_dwordx4 v[196:197], off
	v_lshl_add_u64 v[196:197], v[232:233], 0, s[26:27]
	s_mov_b32 m0, s60
	s_nop 0
	global_load_lds_dwordx4 v[196:197], off
	s_waitcnt vmcnt(8)
	s_waitcnt lgkmcnt(0)
	s_barrier
	s_setprio 1
	s_waitcnt lgkmcnt(0)
	v_mfma_f32_16x16x32_bf16 v[60:63], v[128:131], v[178:181], v[60:63]
	v_mfma_f32_16x16x32_bf16 v[56:59], v[136:139], v[178:181], v[56:59]
	v_mfma_f32_16x16x32_bf16 v[44:47], v[128:131], v[190:193], v[44:47]
	v_mfma_f32_16x16x32_bf16 v[40:43], v[136:139], v[190:193], v[40:43]
	v_mfma_f32_16x16x32_bf16 v[28:31], v[128:131], v[206:209], v[28:31]
	v_mfma_f32_16x16x32_bf16 v[24:27], v[136:139], v[206:209], v[24:27]
	v_mfma_f32_16x16x32_bf16 v[12:15], v[128:131], v[220:223], v[12:15]
	v_mfma_f32_16x16x32_bf16 v[8:11], v[136:139], v[220:223], v[8:11]
	v_mfma_f32_16x16x32_bf16 v[60:63], v[132:135], v[184:187], v[60:63]
	v_mfma_f32_16x16x32_bf16 v[56:59], v[140:143], v[184:187], v[56:59]
	v_mfma_f32_16x16x32_bf16 v[44:47], v[132:135], v[200:203], v[44:47]
	v_mfma_f32_16x16x32_bf16 v[40:43], v[140:143], v[200:203], v[40:43]
	v_mfma_f32_16x16x32_bf16 v[28:31], v[132:135], v[214:217], v[28:31]
	v_mfma_f32_16x16x32_bf16 v[24:27], v[140:143], v[214:217], v[24:27]
	v_mfma_f32_16x16x32_bf16 v[12:15], v[132:135], v[226:229], v[12:15]
	v_mfma_f32_16x16x32_bf16 v[8:11], v[140:143], v[226:229], v[8:11]
	s_setprio 0
	s_setprio 1
	v_mfma_f32_16x16x32_bf16 v[52:55], v[144:147], v[178:181], v[52:55]
	v_mfma_f32_16x16x32_bf16 v[48:51], v[152:155], v[178:181], v[48:51]
	v_mfma_f32_16x16x32_bf16 v[36:39], v[144:147], v[190:193], v[36:39]
	v_mfma_f32_16x16x32_bf16 v[32:35], v[152:155], v[190:193], v[32:35]
	v_mfma_f32_16x16x32_bf16 v[20:23], v[144:147], v[206:209], v[20:23]
	v_mfma_f32_16x16x32_bf16 v[16:19], v[152:155], v[206:209], v[16:19]
	v_mfma_f32_16x16x32_bf16 v[4:7], v[144:147], v[220:223], v[4:7]
	v_mfma_f32_16x16x32_bf16 v[0:3], v[152:155], v[220:223], v[0:3]
	v_mfma_f32_16x16x32_bf16 v[52:55], v[148:151], v[184:187], v[52:55]
	v_mfma_f32_16x16x32_bf16 v[48:51], v[156:159], v[184:187], v[48:51]
	v_mfma_f32_16x16x32_bf16 v[36:39], v[148:151], v[200:203], v[36:39]
	v_mfma_f32_16x16x32_bf16 v[32:35], v[156:159], v[200:203], v[32:35]
	v_mfma_f32_16x16x32_bf16 v[20:23], v[148:151], v[214:217], v[20:23]
	v_mfma_f32_16x16x32_bf16 v[16:19], v[156:159], v[214:217], v[16:19]
	v_mfma_f32_16x16x32_bf16 v[4:7], v[148:151], v[226:229], v[4:7]
	v_mfma_f32_16x16x32_bf16 v[0:3], v[156:159], v[226:229], v[0:3]
	s_setprio 0
	s_barrier
	s_add_u32 s50, s50, 0x100
	s_addc_u32 s51, s51, 0
	s_add_u32 s47, s47, 0x100
	s_addc_u32 s67, s67, 0
	s_cmp_ge_i32 s68, s35
	s_mov_b32 s52, s68
	s_cbranch_scc0 .LBB0_433

; __device__ __forceinline__ void load_row_stats(const float* sp, int row0, RowStats& r) {
; #pragma unroll
;     for (int ai = 0; ai < 2; ++ai) { asm volatile("" ::: "memory");
; #pragma unroll
;         for (int m = 0; m < 4; ++m) { const float* p = sp + (size_t)(row0 + ai * HALF + m * 16) * 8; const f32x4 a = *(const f32x4*)p, b = *(const f32x4*)(p + 4);
;             const float s1 = (a[0] + a[2]) + (b[0] + b[2]), s2 = (a[1] + a[3]) + (b[1] + b[3]); const float mu = s1 * (1.f / 1024.f); const float var = s2 * (1.f / 1024.f) - mu * mu;
;             r.mu[ai][m] = mu; r.rs[ai][m] = __builtin_amdgcn_rsqf(__builtin_fmaxf(var, 0.f) + 1e-5f); } }
;     __device__ __forceinline__ void operator()(const f32x4 (&acc)[2][2][4][2], const Unit& u, int wr, int wc, int fr_in, int fq_in) const {
;     ...
;         RowStats rst; load_row_stats(sp, row0, rst); f32x4 csv[2][2], cbv[2][2];
.LBB0_436:
	s_lshl_b32 s8, s46, 8
	v_mov_b32_e32 v228, v183
	v_mov_b32_e32 v128, v189
	s_add_i32 s8, s8, s49
	s_nop 0
	v_add_u32_e32 v220, s8, v228
	v_ashrrev_i32_e32 v221, 31, v220
	s_cselect_b32 s99, 1, 0
	v_readfirstlane_b32 s98, v254
	v_and_b32_e32 v130, 0xffffff00, v220
	s_nop 0
	s_cmpk_lt_u32 s98, 0x100
	s_cbranch_scc0 .Lrs0_skip
	v_pk_add_f32 v[130:131], v[246:247], v[248:249]
	v_pk_add_f32 v[134:135], v[250:251], v[252:253]
	s_nop 0
	v_pk_add_f32 v[130:131], v[134:135], v[130:131]
	s_nop 0
	v_pk_mul_f32 v[130:131], v[130:131], s[34:35] op_sel_hi:[1,0]
	v_lshlrev_b32_e32 v132, 3, v254
	v_add_u32_e32 v132, 0x22400, v132
	ds_write_b64 v132, v[130:131]

; template <class Epi, class Sched, bool ALIGN_EPI = false, bool SP2 = false>
; __device__ __forceinline__ void gemm_phase(PG8_LAS unsigned char* lds, const Gemm g, const Sched& S, const Epi& E) {
;     ...
;         const char* nA = has_next ? (const char*)g.A + (size_t)nxt.pm * tstepA : cA; const char* nB = has_next ? (const char*)g.Bt + (size_t)nxt.pn * tstepB : cB;
;         for (int t = 0; t < nt; t += 2) {
;             const bool last = (t == nt - 2);
;             const char* a1 = cA + (long)(t + 1) * kstepA;
;             const char* a2 = last ? nA : cA + (long)(t + 2) * kstepA; const char* b2 = last ? nB : cB + (long)(t + 2) * kstep;
;     ...
; #pragma unroll
;         for (int a = 0; a < 2; ++a)
; #pragma unroll
;             for (int b = 0; b < 2; ++b)
; #pragma unroll
;                 for (int m = 0; m < 4; ++m)
; #pragma unroll
;                     for (int n = 0; n < 2; ++n) acc[a][b][m][n] = (f32x4){0.f, 0.f, 0.f, 0.f};
;         cur = nxt; cA = nA; cB = nB; ++ui;
.LBB0_1255:
	s_ashr_i32 s37, s36, 31
	s_lshl_b64 s[40:41], s[36:37], 19
	s_add_u32 s40, s9, s40
	s_addc_u32 s41, s14, s41
	s_ashr_i32 s35, s34, 31
	s_lshl_b64 s[42:43], s[34:35], 19
	s_add_u32 s42, s15, s42
	v_mov_b32_e32 v143, 0
	s_addc_u32 s43, s16, s43
	s_andn2_b64 vcc, exec, s[26:27]
	v_mov_b32_e32 v142, v143
	v_mov_b32_e32 v141, v143
	v_mov_b32_e32 v140, v143
	v_mov_b32_e32 v123, v143
	v_mov_b32_e32 v122, v143
	v_mov_b32_e32 v121, v143
	v_mov_b32_e32 v120, v143
	v_mov_b32_e32 v107, v143
	v_mov_b32_e32 v106, v143
	v_mov_b32_e32 v105, v143
	v_mov_b32_e32 v104, v143
	v_mov_b32_e32 v99, v143
	v_mov_b32_e32 v98, v143
	v_mov_b32_e32 v97, v143
	v_mov_b32_e32 v96, v143
	v_mov_b32_e32 v91, v143
	v_mov_b32_e32 v90, v143
	v_mov_b32_e32 v89, v143
	v_mov_b32_e32 v88, v143
	v_mov_b32_e32 v83, v143
	v_mov_b32_e32 v82, v143
	v_mov_b32_e32 v81, v143
	v_mov_b32_e32 v80, v143
	v_mov_b32_e32 v75, v143
	v_mov_b32_e32 v74, v143
	v_mov_b32_e32 v73, v143
	v_mov_b32_e32 v72, v143
	v_mov_b32_e32 v67, v143
	v_mov_b32_e32 v66, v143
	v_mov_b32_e32 v65, v143
	v_mov_b32_e32 v64, v143
	v_mov_b32_e32 v147, v143
	v_mov_b32_e32 v146, v143
	v_mov_b32_e32 v145, v143
	v_mov_b32_e32 v144, v143
	v_mov_b32_e32 v127, v143
	v_mov_b32_e32 v126, v143
	v_mov_b32_e32 v125, v143
	v_mov_b32_e32 v124, v143
	v_mov_b32_e32 v111, v143
	v_mov_b32_e32 v110, v143
	v_mov_b32_e32 v109, v143
	v_mov_b32_e32 v108, v143
	v_mov_b32_e32 v103, v143
	v_mov_b32_e32 v102, v143
	v_mov_b32_e32 v101, v143
	v_mov_b32_e32 v100, v143
	v_mov_b32_e32 v95, v143
	v_mov_b32_e32 v94, v143
	v_mov_b32_e32 v93, v143
	v_mov_b32_e32 v92, v143
	v_mov_b32_e32 v87, v143
	v_mov_b32_e32 v86, v143
	v_mov_b32_e32 v85, v143
	v_mov_b32_e32 v84, v143
	v_mov_b32_e32 v79, v143
	v_mov_b32_e32 v78, v143
	v_mov_b32_e32 v77, v143
	v_mov_b32_e32 v76, v143
	v_mov_b32_e32 v71, v143
	v_mov_b32_e32 v70, v143
	v_mov_b32_e32 v69, v143
	v_mov_b32_e32 v68, v143
	v_mov_b32_e32 v59, v143
	v_mov_b32_e32 v58, v143
	v_mov_b32_e32 v57, v143
	v_mov_b32_e32 v56, v143
	v_mov_b32_e32 v51, v143
	v_mov_b32_e32 v50, v143
	v_mov_b32_e32 v49, v143
	v_mov_b32_e32 v48, v143
	v_mov_b32_e32 v43, v143
	v_mov_b32_e32 v42, v143
	v_mov_b32_e32 v41, v143
	v_mov_b32_e32 v40, v143
	v_mov_b32_e32 v35, v143
	v_mov_b32_e32 v34, v143
	v_mov_b32_e32 v33, v143
	v_mov_b32_e32 v32, v143
	v_mov_b32_e32 v27, v143
	v_mov_b32_e32 v26, v143
	v_mov_b32_e32 v25, v143
	v_mov_b32_e32 v24, v143
	v_mov_b32_e32 v19, v143
	v_mov_b32_e32 v18, v143
	v_mov_b32_e32 v17, v143
	v_mov_b32_e32 v16, v143
	v_mov_b32_e32 v11, v143
	v_mov_b32_e32 v10, v143
	v_mov_b32_e32 v9, v143
	v_mov_b32_e32 v8, v143
	v_mov_b32_e32 v7, v143
	v_mov_b32_e32 v6, v143
	v_mov_b32_e32 v5, v143
	v_mov_b32_e32 v4, v143
	v_mov_b32_e32 v63, v143
	v_mov_b32_e32 v62, v143
	v_mov_b32_e32 v61, v143
	v_mov_b32_e32 v60, v143
	v_mov_b32_e32 v55, v143
	v_mov_b32_e32 v54, v143
	v_mov_b32_e32 v53, v143
	v_mov_b32_e32 v52, v143
	v_mov_b32_e32 v47, v143
	v_mov_b32_e32 v46, v143
	v_mov_b32_e32 v45, v143
	v_mov_b32_e32 v44, v143
	v_mov_b32_e32 v39, v143
	v_mov_b32_e32 v38, v143
	v_mov_b32_e32 v37, v143
	v_mov_b32_e32 v36, v143
	v_mov_b32_e32 v31, v143
	v_mov_b32_e32 v30, v143
	v_mov_b32_e32 v29, v143
	v_mov_b32_e32 v28, v143
	v_mov_b32_e32 v23, v143
	v_mov_b32_e32 v22, v143
	v_mov_b32_e32 v21, v143
	v_mov_b32_e32 v20, v143
	v_mov_b32_e32 v15, v143
	v_mov_b32_e32 v14, v143
	v_mov_b32_e32 v13, v143
	v_mov_b32_e32 v12, v143
	v_mov_b32_e32 v3, v143
	v_mov_b32_e32 v2, v143
	v_mov_b32_e32 v1, v143
	v_mov_b32_e32 v0, v143
	s_cbranch_vccnz .LBB0_1258
	s_and_b64 s[50:51], s[38:39], exec
	s_cselect_b32 s35, s41, s47
	s_cselect_b32 s37, s40, s46
	s_cselect_b32 s64, s43, s49
	s_cselect_b32 s65, s42, s48
	s_add_u32 s46, s46, 0x40080
	s_addc_u32 s47, s47, 0
	s_add_u32 s66, s48, 0x100
	v_mov_b32_e32 v0, 0
	s_addc_u32 s67, s49, 0
	s_mov_b32 s48, 0
	v_mov_b32_e32 v1, v0
	v_mov_b32_e32 v2, v0
	v_mov_b32_e32 v3, v0
	v_mov_b32_e32 v12, v0
	v_mov_b32_e32 v13, v0
	v_mov_b32_e32 v14, v0
	v_mov_b32_e32 v15, v0
	v_mov_b32_e32 v20, v0
	v_mov_b32_e32 v21, v0
	v_mov_b32_e32 v22, v0
	v_mov_b32_e32 v23, v0
	v_mov_b32_e32 v28, v0
	v_mov_b32_e32 v29, v0
	v_mov_b32_e32 v30, v0
	v_mov_b32_e32 v31, v0
	v_mov_b32_e32 v36, v0
	v_mov_b32_e32 v37, v0
	v_mov_b32_e32 v38, v0
	v_mov_b32_e32 v39, v0
	v_mov_b32_e32 v44, v0
	v_mov_b32_e32 v45, v0
	v_mov_b32_e32 v46, v0
	v_mov_b32_e32 v47, v0
	v_mov_b32_e32 v52, v0
	v_mov_b32_e32 v53, v0
	v_mov_b32_e32 v54, v0
	v_mov_b32_e32 v55, v0
	v_mov_b32_e32 v60, v0
	v_mov_b32_e32 v61, v0
	v_mov_b32_e32 v62, v0
	v_mov_b32_e32 v63, v0
	v_mov_b32_e32 v4, v0
	v_mov_b32_e32 v5, v0
	v_mov_b32_e32 v6, v0
	v_mov_b32_e32 v7, v0
	v_mov_b32_e32 v8, v0
	v_mov_b32_e32 v9, v0
	v_mov_b32_e32 v10, v0
	v_mov_b32_e32 v11, v0
	v_mov_b32_e32 v16, v0
	v_mov_b32_e32 v17, v0
	v_mov_b32_e32 v18, v0
	v_mov_b32_e32 v19, v0
	v_mov_b32_e32 v24, v0
	v_mov_b32_e32 v25, v0
	v_mov_b32_e32 v26, v0
	v_mov_b32_e32 v27, v0
	v_mov_b32_e32 v32, v0
	v_mov_b32_e32 v33, v0
	v_mov_b32_e32 v34, v0
	v_mov_b32_e32 v35, v0
	v_mov_b32_e32 v40, v0
	v_mov_b32_e32 v41, v0
	v_mov_b32_e32 v42, v0
	v_mov_b32_e32 v43, v0
	v_mov_b32_e32 v48, v0
	v_mov_b32_e32 v49, v0
	v_mov_b32_e32 v50, v0
	v_mov_b32_e32 v51, v0
	v_mov_b32_e32 v56, v0
	v_mov_b32_e32 v57, v0
	v_mov_b32_e32 v58, v0
	v_mov_b32_e32 v59, v0
	v_mov_b32_e32 v68, v0
	v_mov_b32_e32 v69, v0
	v_mov_b32_e32 v70, v0
	v_mov_b32_e32 v71, v0
	v_mov_b32_e32 v76, v0
	v_mov_b32_e32 v77, v0
	v_mov_b32_e32 v78, v0
	v_mov_b32_e32 v79, v0
	v_mov_b32_e32 v84, v0
	v_mov_b32_e32 v85, v0
	v_mov_b32_e32 v86, v0
	v_mov_b32_e32 v87, v0
	v_mov_b32_e32 v92, v0
	v_mov_b32_e32 v93, v0
	v_mov_b32_e32 v94, v0
	v_mov_b32_e32 v95, v0
	v_mov_b32_e32 v100, v0
	v_mov_b32_e32 v101, v0
	v_mov_b32_e32 v102, v0
	v_mov_b32_e32 v103, v0
	v_mov_b32_e32 v108, v0
	v_mov_b32_e32 v109, v0
	v_mov_b32_e32 v110, v0
	v_mov_b32_e32 v111, v0
	v_mov_b32_e32 v124, v0
	v_mov_b32_e32 v125, v0
	v_mov_b32_e32 v126, v0
	v_mov_b32_e32 v127, v0
	v_mov_b32_e32 v144, v0
	v_mov_b32_e32 v145, v0
	v_mov_b32_e32 v146, v0
	v_mov_b32_e32 v147, v0
	v_mov_b32_e32 v64, v0
	v_mov_b32_e32 v65, v0
	v_mov_b32_e32 v66, v0
	v_mov_b32_e32 v67, v0
	v_mov_b32_e32 v72, v0
	v_mov_b32_e32 v73, v0
	v_mov_b32_e32 v74, v0
	v_mov_b32_e32 v75, v0
	v_mov_b32_e32 v80, v0
	v_mov_b32_e32 v81, v0
	v_mov_b32_e32 v82, v0
	v_mov_b32_e32 v83, v0
	v_mov_b32_e32 v88, v0
	v_mov_b32_e32 v89, v0
	v_mov_b32_e32 v90, v0
	v_mov_b32_e32 v91, v0
	v_mov_b32_e32 v96, v0
	v_mov_b32_e32 v97, v0
	v_mov_b32_e32 v98, v0
	v_mov_b32_e32 v99, v0
	v_mov_b32_e32 v104, v0
	v_mov_b32_e32 v105, v0
	v_mov_b32_e32 v106, v0
	v_mov_b32_e32 v107, v0
	v_mov_b32_e32 v120, v0
	v_mov_b32_e32 v121, v0
	v_mov_b32_e32 v122, v0
	v_mov_b32_e32 v123, v0
	v_mov_b32_e32 v140, v0
	v_mov_b32_e32 v141, v0
	v_mov_b32_e32 v142, v0
	v_mov_b32_e32 v143, v0
	v_readfirstlane_b32 s98, v254
	s_lshl_b32 s99, s44, 8
	s_nop 0
	s_cmpk_lt_u32 s98, 0x100
	s_cbranch_scc0 .Lrs2_nopre
; #define PG8_STAGE(bufoff, gbase, voff) do { _Pragma("unroll") for (int _i = 0; _i < 2; ++_i) \
;         __builtin_amdgcn_global_load_lds((const unsigned*)((const char*)(gbase) + (voff)[_i]), (PG8_LAS unsigned*)(lds + (bufoff) + ldsw + _i * 8192), 16, 0, 0); } while (0)
; #define PG8_LDA(dst, b, h) do { _Pragma("unroll") for (int m = 0; m < 4; ++m) _Pragma("unroll") for (int k = 0; k < 2; ++k) dst[m][k] = *(const PG8_LAS bf16x8*)(lds + PG8_SA(b, h) + aoff + m * 2048 + k * 1024); } while (0)
; #define PG8_WAIT_V(n) asm volatile("s_waitcnt vmcnt(" #n ")" ::: "memory")
; #define PG8_WAIT_L(n) asm volatile("s_waitcnt lgkmcnt(" #n ")" ::: "memory")
; __device__ __forceinline__ void load_row_stats(const float* sp, int row0, RowStats& r) {
; #pragma unroll
;     for (int ai = 0; ai < 2; ++ai) { asm volatile("" ::: "memory");
; #pragma unroll
;         for (int m = 0; m < 4; ++m) { const float* p = sp + (size_t)(row0 + ai * HALF + m * 16) * 8; const f32x4 a = *(const f32x4*)p, b = *(const f32x4*)(p + 4);
;             const float s1 = (a[0] + a[2]) + (b[0] + b[2]), s2 = (a[1] + a[3]) + (b[1] + b[3]); const float mu = s1 * (1.f / 1024.f); const float var = s2 * (1.f / 1024.f) - mu * mu;
;             r.mu[ai][m] = mu; r.rs[ai][m] = __builtin_amdgcn_rsqf(__builtin_fmaxf(var, 0.f) + 1e-5f); } }
; template <class Epi, class Sched, bool ALIGN_EPI = false, bool SP2 = false>
; __device__ __forceinline__ void gemm_phase(PG8_LAS unsigned char* lds, const Gemm g, const Sched& S, const Epi& E) {
;     ...
;             const char* a1 = cA + (long)(t + 1) * kstepA;
;             const char* a2 = last ? nA : cA + (long)(t + 2) * kstepA; const char* b2 = last ? nB : cB + (long)(t + 2) * kstep;
;             const char* a3 = a2 + kstepA; const char* b3 = b2 + kstep;
;             if (last && has_next) S.a_ready(nxt);
;             if constexpr (SP2) {
;             PG8_LDB(B0, 0, 0); PG8_LDB(B1, 0, 1); PG8_SCHED; PG8_LDA(At, 0, 0); PG8_STAGE(PG8_SA(1, 1), a1 + hstepA, voffA);
;             PG8_WAIT_V(8); PG8_WAIT_L(0); PG8_BAR; PG8_MMA(0, 0, At, B0); PG8_MMA(0, 1, At, B1); PG8_BAR; PG8_SCHED;
;             PG8_LDA(At, 0, 1); PG8_STAGE(PG8_SB(0, 0), b2, voffB); PG8_STAGE(PG8_SB(0, 1), b2 + hstepB, voffB); PG8_STAGE(PG8_SA(0, 0), a2, voffA);
;             PG8_WAIT_V(8); PG8_WAIT_L(0); PG8_BAR; PG8_MMA(1, 0, At, B0); PG8_MMA(1, 1, At, B1); PG8_BAR; PG8_SCHED;
	v_add_u32_e32 v244, s99, v254
	v_mov_b32_e32 v245, 0
	v_lshlrev_b64 v[244:245], 5, v[244:245]
	v_lshl_add_u64 v[244:245], s[10:11], 0, v[244:245]
	global_load_dwordx4 v[246:249], v[244:245], off offset:16
	global_load_dwordx4 v[250:253], v[244:245], off
.Lrs2_nopre:
.LBB0_1257:
	ds_read_b128 v[112:115], v199
	ds_read_b128 v[116:119], v199 offset:1024
	ds_read_b128 v[128:131], v199 offset:2048
	ds_read_b128 v[132:135], v199 offset:3072
	ds_read_b128 v[136:139], v203
	ds_read_b128 v[148:151], v203 offset:1024
	ds_read_b128 v[152:155], v203 offset:2048
	ds_read_b128 v[156:159], v203 offset:3072
	s_add_i32 s68, s48, 2
	s_add_u32 s49, s46, 0xfffc0080
	s_addc_u32 s50, s47, -1
	s_cmp_eq_u32 s58, s48
	s_cselect_b32 s48, s65, s66
	s_cselect_b32 s51, s35, s50
	s_cselect_b32 s50, s37, s49
	s_cselect_b32 s49, s64, s67
	v_lshl_add_u64 v[176:177], s[46:47], 0, v[168:169]
	s_add_i32 m0, s20, 0xc000
	ds_read_b128 v[180:183], v217
	ds_read_b128 v[186:189], v217 offset:1024
	ds_read_b128 v[192:195], v217 offset:2048
	ds_read_b128 v[204:207], v217 offset:3072
	ds_read_b128 v[208:211], v217 offset:4096
	ds_read_b128 v[212:215], v217 offset:5120
	ds_read_b128 v[218:221], v217 offset:6144
	ds_read_b128 v[222:225], v217 offset:7168
	global_load_lds_dwordx4 v[176:177], off
	v_lshl_add_u64 v[176:177], s[46:47], 0, v[170:171]
	s_add_i32 m0, s20, 0xe000
	s_nop 0
	global_load_lds_dwordx4 v[176:177], off
	s_waitcnt vmcnt(8)
	s_waitcnt lgkmcnt(0)
	s_barrier
	s_setprio 1
	s_waitcnt lgkmcnt(0)
	v_mfma_f32_16x16x32_bf16 v[140:143], v[112:115], v[180:183], v[140:143]
	v_mfma_f32_16x16x32_bf16 v[120:123], v[128:131], v[180:183], v[120:123]
	v_mfma_f32_16x16x32_bf16 v[104:107], v[112:115], v[192:195], v[104:107]
	v_mfma_f32_16x16x32_bf16 v[96:99], v[128:131], v[192:195], v[96:99]
	v_mfma_f32_16x16x32_bf16 v[88:91], v[112:115], v[208:211], v[88:91]
	v_mfma_f32_16x16x32_bf16 v[80:83], v[128:131], v[208:211], v[80:83]
	v_mfma_f32_16x16x32_bf16 v[72:75], v[112:115], v[218:221], v[72:75]
	v_mfma_f32_16x16x32_bf16 v[64:67], v[128:131], v[218:221], v[64:67]
	v_mfma_f32_16x16x32_bf16 v[140:143], v[116:119], v[186:189], v[140:143]
	v_mfma_f32_16x16x32_bf16 v[120:123], v[132:135], v[186:189], v[120:123]
	v_mfma_f32_16x16x32_bf16 v[104:107], v[116:119], v[204:207], v[104:107]
	v_mfma_f32_16x16x32_bf16 v[96:99], v[132:135], v[204:207], v[96:99]
	v_mfma_f32_16x16x32_bf16 v[88:91], v[116:119], v[212:215], v[88:91]
	v_mfma_f32_16x16x32_bf16 v[80:83], v[132:135], v[212:215], v[80:83]
	v_mfma_f32_16x16x32_bf16 v[72:75], v[116:119], v[222:225], v[72:75]
	v_mfma_f32_16x16x32_bf16 v[64:67], v[132:135], v[222:225], v[64:67]
	s_setprio 0
	s_setprio 1
	v_mfma_f32_16x16x32_bf16 v[144:147], v[136:139], v[180:183], v[144:147]
	v_mfma_f32_16x16x32_bf16 v[124:127], v[152:155], v[180:183], v[124:127]
	v_mfma_f32_16x16x32_bf16 v[108:111], v[136:139], v[192:195], v[108:111]
	v_mfma_f32_16x16x32_bf16 v[100:103], v[152:155], v[192:195], v[100:103]
	v_mfma_f32_16x16x32_bf16 v[92:95], v[136:139], v[208:211], v[92:95]
	v_mfma_f32_16x16x32_bf16 v[84:87], v[152:155], v[208:211], v[84:87]
	v_mfma_f32_16x16x32_bf16 v[76:79], v[136:139], v[218:221], v[76:79]
	v_mfma_f32_16x16x32_bf16 v[68:71], v[152:155], v[218:221], v[68:71]
	v_mfma_f32_16x16x32_bf16 v[144:147], v[148:151], v[186:189], v[144:147]
	v_mfma_f32_16x16x32_bf16 v[124:127], v[156:159], v[186:189], v[124:127]
	v_mfma_f32_16x16x32_bf16 v[108:111], v[148:151], v[204:207], v[108:111]
	v_mfma_f32_16x16x32_bf16 v[100:103], v[156:159], v[204:207], v[100:103]
	v_mfma_f32_16x16x32_bf16 v[92:95], v[148:151], v[212:215], v[92:95]
	v_mfma_f32_16x16x32_bf16 v[84:87], v[156:159], v[212:215], v[84:87]
	v_mfma_f32_16x16x32_bf16 v[76:79], v[148:151], v[222:225], v[76:79]
	v_mfma_f32_16x16x32_bf16 v[68:71], v[156:159], v[222:225], v[68:71]
	s_setprio 0
	s_barrier
	s_add_i32 s69, s62, s17
	v_lshl_add_u64 v[176:177], s[48:49], 0, v[164:165]
	s_mov_b32 m0, s69
	ds_read_b128 v[180:183], v217 offset:16384
	ds_read_b128 v[186:189], v217 offset:17408
	ds_read_b128 v[192:195], v217 offset:18432
	ds_read_b128 v[204:207], v217 offset:19456
	ds_read_b128 v[208:211], v217 offset:20480
	ds_read_b128 v[212:215], v217 offset:21504
	ds_read_b128 v[218:221], v217 offset:22528
	ds_read_b128 v[222:225], v217 offset:23552
	global_load_lds_dwordx4 v[176:177], off
	s_add_i32 m0, s69, 0x2000
	s_add_u32 s70, s48, 0x40000
	v_lshl_add_u64 v[196:197], s[48:49], 0, v[160:161]
	s_addc_u32 s71, s49, 0
	s_add_i32 s69, s63, s17
	global_load_lds_dwordx4 v[196:197], off
	v_lshl_add_u64 v[200:201], s[70:71], 0, v[164:165]
	s_mov_b32 m0, s69
	v_lshl_add_u64 v[226:227], s[50:51], 0, v[162:163]
	global_load_lds_dwordx4 v[200:201], off
	v_lshl_add_u64 v[200:201], s[70:71], 0, v[160:161]
	s_add_i32 m0, s69, 0x2000
	s_nop 0
	global_load_lds_dwordx4 v[200:201], off
	v_lshl_add_u64 v[200:201], s[50:51], 0, v[166:167]
	s_mov_b32 m0, s20
	s_nop 0
	global_load_lds_dwordx4 v[200:201], off
	s_mov_b32 m0, s21
	s_nop 0
	global_load_lds_dwordx4 v[226:227], off
	s_waitcnt vmcnt(8)
	s_waitcnt lgkmcnt(0)
	s_barrier
; #define PG8_STAGE(bufoff, gbase, voff) do { _Pragma("unroll") for (int _i = 0; _i < 2; ++_i) \
;         __builtin_amdgcn_global_load_lds((const unsigned*)((const char*)(gbase) + (voff)[_i]), (PG8_LAS unsigned*)(lds + (bufoff) + ldsw + _i * 8192), 16, 0, 0); } while (0)
; #define PG8_LDA(dst, b, h) do { _Pragma("unroll") for (int m = 0; m < 4; ++m) _Pragma("unroll") for (int k = 0; k < 2; ++k) dst[m][k] = *(const PG8_LAS bf16x8*)(lds + PG8_SA(b, h) + aoff + m * 2048 + k * 1024); } while (0)
; #define PG8_LDB(dst, b, h) do { _Pragma("unroll") for (int n = 0; n < 2; ++n) _Pragma("unroll") for (int k = 0; k < 2; ++k) dst[n][k] = *(const PG8_LAS bf16x8*)(lds + PG8_SB(b, h) + boff + n * 2048 + k * 1024); } while (0)
; #define PG8_MMA(ai, bj, At, Bt) do { __builtin_amdgcn_s_setprio(1); _Pragma("unroll") for (int m = 0; m < 4; ++m) _Pragma("unroll") for (int n = 0; n < 2; ++n) _Pragma("unroll") for (int k = 0; k < 2; ++k) \
;         acc[ai][bj][m][n] = __builtin_amdgcn_mfma_f32_16x16x32_bf16(Bt[n][k], At[m][k], acc[ai][bj][m][n], 0, 0, 0); __builtin_amdgcn_s_setprio(0); } while (0)
; #define PG8_WAIT_V(n) asm volatile("s_waitcnt vmcnt(" #n ")" ::: "memory")
; #define PG8_WAIT_L(n) asm volatile("s_waitcnt lgkmcnt(" #n ")" ::: "memory")
; #define PG8_BAR __builtin_amdgcn_s_barrier()
; #define PG8_SCHED __builtin_amdgcn_sched_barrier(0)
; template <class Epi, class Sched, bool ALIGN_EPI = false, bool SP2 = false>
; __device__ __forceinline__ void gemm_phase(PG8_LAS unsigned char* lds, const Gemm g, const Sched& S, const Epi& E) {
;     ...
;             PG8_WAIT_V(8); PG8_WAIT_L(0); PG8_BAR; PG8_MMA(1, 0, At, B0); PG8_MMA(1, 1, At, B1); PG8_BAR; PG8_SCHED;
;             PG8_LDB(B0, 1, 0); PG8_LDB(B1, 1, 1); PG8_SCHED; PG8_LDA(At, 1, 0); PG8_STAGE(PG8_SA(0, 1), a2 + hstepA, voffA);
;             PG8_WAIT_V(8); PG8_WAIT_L(0); PG8_BAR; PG8_MMA(0, 0, At, B0); PG8_MMA(0, 1, At, B1); PG8_BAR; PG8_SCHED;
;             PG8_LDA(At, 1, 1); PG8_STAGE(PG8_SB(1, 0), b3, voffB); PG8_STAGE(PG8_SB(1, 1), b3 + hstepB, voffB); PG8_STAGE(PG8_SA(1, 0), a3, voffA);
	s_setprio 1
	s_waitcnt lgkmcnt(0)
	v_mfma_f32_16x16x32_bf16 v[56:59], v[112:115], v[180:183], v[56:59]
	v_mfma_f32_16x16x32_bf16 v[48:51], v[128:131], v[180:183], v[48:51]
	v_mfma_f32_16x16x32_bf16 v[40:43], v[112:115], v[192:195], v[40:43]
	v_mfma_f32_16x16x32_bf16 v[32:35], v[128:131], v[192:195], v[32:35]
	v_mfma_f32_16x16x32_bf16 v[24:27], v[112:115], v[208:211], v[24:27]
	v_mfma_f32_16x16x32_bf16 v[16:19], v[128:131], v[208:211], v[16:19]
	v_mfma_f32_16x16x32_bf16 v[8:11], v[112:115], v[218:221], v[8:11]
	v_mfma_f32_16x16x32_bf16 v[4:7], v[128:131], v[218:221], v[4:7]
	v_mfma_f32_16x16x32_bf16 v[56:59], v[116:119], v[186:189], v[56:59]
	v_mfma_f32_16x16x32_bf16 v[48:51], v[132:135], v[186:189], v[48:51]
	v_mfma_f32_16x16x32_bf16 v[40:43], v[116:119], v[204:207], v[40:43]
	v_mfma_f32_16x16x32_bf16 v[32:35], v[132:135], v[204:207], v[32:35]
	v_mfma_f32_16x16x32_bf16 v[24:27], v[116:119], v[212:215], v[24:27]
	v_mfma_f32_16x16x32_bf16 v[16:19], v[132:135], v[212:215], v[16:19]
	v_mfma_f32_16x16x32_bf16 v[8:11], v[116:119], v[222:225], v[8:11]
	v_mfma_f32_16x16x32_bf16 v[4:7], v[132:135], v[222:225], v[4:7]
	s_setprio 0
	s_setprio 1
	v_mfma_f32_16x16x32_bf16 v[60:63], v[136:139], v[180:183], v[60:63]
	v_mfma_f32_16x16x32_bf16 v[52:55], v[152:155], v[180:183], v[52:55]
	v_mfma_f32_16x16x32_bf16 v[44:47], v[136:139], v[192:195], v[44:47]
	v_mfma_f32_16x16x32_bf16 v[36:39], v[152:155], v[192:195], v[36:39]
	v_mfma_f32_16x16x32_bf16 v[28:31], v[136:139], v[208:211], v[28:31]
	v_mfma_f32_16x16x32_bf16 v[20:23], v[152:155], v[208:211], v[20:23]
	v_mfma_f32_16x16x32_bf16 v[12:15], v[136:139], v[218:221], v[12:15]
	v_mfma_f32_16x16x32_bf16 v[0:3], v[152:155], v[218:221], v[0:3]
	v_mfma_f32_16x16x32_bf16 v[60:63], v[148:151], v[186:189], v[60:63]
	v_mfma_f32_16x16x32_bf16 v[52:55], v[156:159], v[186:189], v[52:55]
	v_mfma_f32_16x16x32_bf16 v[44:47], v[148:151], v[204:207], v[44:47]
	v_mfma_f32_16x16x32_bf16 v[36:39], v[156:159], v[204:207], v[36:39]
	v_mfma_f32_16x16x32_bf16 v[28:31], v[148:151], v[212:215], v[28:31]
	v_mfma_f32_16x16x32_bf16 v[20:23], v[156:159], v[212:215], v[20:23]
	v_mfma_f32_16x16x32_bf16 v[12:15], v[148:151], v[222:225], v[12:15]
	v_mfma_f32_16x16x32_bf16 v[0:3], v[156:159], v[222:225], v[0:3]
	s_setprio 0
	s_barrier
	s_add_i32 s69, 0, 0x18000
	s_add_i32 s70, 0, 0x1c000
	v_add_u32_e32 v132, s69, v191
	v_add_u32_e32 v156, s70, v191
	ds_read_b128 v[112:115], v132
	ds_read_b128 v[116:119], v132 offset:1024
	ds_read_b128 v[128:131], v132 offset:2048
	ds_read_b128 v[132:135], v132 offset:3072
	ds_read_b128 v[136:139], v156
	ds_read_b128 v[148:151], v156 offset:1024
	ds_read_b128 v[152:155], v156 offset:2048
	ds_read_b128 v[156:159], v156 offset:3072
	s_add_u32 s50, s50, 0x40000
	s_addc_u32 s51, s51, 0
	s_mov_b32 m0, s31
	v_lshl_add_u64 v[228:229], s[50:51], 0, v[166:167]
	ds_read_b128 v[180:183], v217 offset:32768
	ds_read_b128 v[186:189], v217 offset:33792
	ds_read_b128 v[192:195], v217 offset:34816
	ds_read_b128 v[204:207], v217 offset:35840
	ds_read_b128 v[208:211], v217 offset:36864
	ds_read_b128 v[212:215], v217 offset:37888
	ds_read_b128 v[218:221], v217 offset:38912
	ds_read_b128 v[222:225], v217 offset:39936
	global_load_lds_dwordx4 v[228:229], off
	v_lshl_add_u64 v[228:229], s[50:51], 0, v[162:163]
	s_mov_b32 m0, s33
	s_nop 0
	global_load_lds_dwordx4 v[228:229], off
	s_waitcnt vmcnt(8)
	s_waitcnt lgkmcnt(0)
	s_barrier
	s_setprio 1
	s_waitcnt lgkmcnt(0)
	v_mfma_f32_16x16x32_bf16 v[140:143], v[112:115], v[180:183], v[140:143]
	v_mfma_f32_16x16x32_bf16 v[120:123], v[128:131], v[180:183], v[120:123]
	v_mfma_f32_16x16x32_bf16 v[104:107], v[112:115], v[192:195], v[104:107]
	v_mfma_f32_16x16x32_bf16 v[96:99], v[128:131], v[192:195], v[96:99]
	v_mfma_f32_16x16x32_bf16 v[88:91], v[112:115], v[208:211], v[88:91]
	v_mfma_f32_16x16x32_bf16 v[80:83], v[128:131], v[208:211], v[80:83]
	v_mfma_f32_16x16x32_bf16 v[72:75], v[112:115], v[218:221], v[72:75]
	v_mfma_f32_16x16x32_bf16 v[64:67], v[128:131], v[218:221], v[64:67]
	v_mfma_f32_16x16x32_bf16 v[140:143], v[116:119], v[186:189], v[140:143]
	v_mfma_f32_16x16x32_bf16 v[120:123], v[132:135], v[186:189], v[120:123]
	v_mfma_f32_16x16x32_bf16 v[104:107], v[116:119], v[204:207], v[104:107]
	v_mfma_f32_16x16x32_bf16 v[96:99], v[132:135], v[204:207], v[96:99]
	v_mfma_f32_16x16x32_bf16 v[88:91], v[116:119], v[212:215], v[88:91]
	v_mfma_f32_16x16x32_bf16 v[80:83], v[132:135], v[212:215], v[80:83]
	v_mfma_f32_16x16x32_bf16 v[72:75], v[116:119], v[222:225], v[72:75]
	v_mfma_f32_16x16x32_bf16 v[64:67], v[132:135], v[222:225], v[64:67]
	s_setprio 0
	s_setprio 1
	v_mfma_f32_16x16x32_bf16 v[144:147], v[136:139], v[180:183], v[144:147]
	v_mfma_f32_16x16x32_bf16 v[124:127], v[152:155], v[180:183], v[124:127]
	v_mfma_f32_16x16x32_bf16 v[108:111], v[136:139], v[192:195], v[108:111]
	v_mfma_f32_16x16x32_bf16 v[100:103], v[152:155], v[192:195], v[100:103]
	v_mfma_f32_16x16x32_bf16 v[92:95], v[136:139], v[208:211], v[92:95]
	v_mfma_f32_16x16x32_bf16 v[84:87], v[152:155], v[208:211], v[84:87]
	v_mfma_f32_16x16x32_bf16 v[76:79], v[136:139], v[218:221], v[76:79]
	v_mfma_f32_16x16x32_bf16 v[68:71], v[152:155], v[218:221], v[68:71]
	v_mfma_f32_16x16x32_bf16 v[144:147], v[148:151], v[186:189], v[144:147]
	v_mfma_f32_16x16x32_bf16 v[124:127], v[156:159], v[186:189], v[124:127]
	v_mfma_f32_16x16x32_bf16 v[108:111], v[148:151], v[204:207], v[108:111]
	v_mfma_f32_16x16x32_bf16 v[100:103], v[156:159], v[204:207], v[100:103]
	v_mfma_f32_16x16x32_bf16 v[92:95], v[148:151], v[212:215], v[92:95]
	v_mfma_f32_16x16x32_bf16 v[84:87], v[156:159], v[212:215], v[84:87]
	v_mfma_f32_16x16x32_bf16 v[76:79], v[148:151], v[222:225], v[76:79]
	v_mfma_f32_16x16x32_bf16 v[68:71], v[156:159], v[222:225], v[68:71]
	s_setprio 0
	s_barrier
; #define PG8_STAGE(bufoff, gbase, voff) do { _Pragma("unroll") for (int _i = 0; _i < 2; ++_i) \
;         __builtin_amdgcn_global_load_lds((const unsigned*)((const char*)(gbase) + (voff)[_i]), (PG8_LAS unsigned*)(lds + (bufoff) + ldsw + _i * 8192), 16, 0, 0); } while (0)
; #define PG8_LDA(dst, b, h) do { _Pragma("unroll") for (int m = 0; m < 4; ++m) _Pragma("unroll") for (int k = 0; k < 2; ++k) dst[m][k] = *(const PG8_LAS bf16x8*)(lds + PG8_SA(b, h) + aoff + m * 2048 + k * 1024); } while (0)
; #define PG8_MMA(ai, bj, At, Bt) do { __builtin_amdgcn_s_setprio(1); _Pragma("unroll") for (int m = 0; m < 4; ++m) _Pragma("unroll") for (int n = 0; n < 2; ++n) _Pragma("unroll") for (int k = 0; k < 2; ++k) \
;         acc[ai][bj][m][n] = __builtin_amdgcn_mfma_f32_16x16x32_bf16(Bt[n][k], At[m][k], acc[ai][bj][m][n], 0, 0, 0); __builtin_amdgcn_s_setprio(0); } while (0)
; #define PG8_WAIT_V(n) asm volatile("s_waitcnt vmcnt(" #n ")" ::: "memory")
; #define PG8_WAIT_L(n) asm volatile("s_waitcnt lgkmcnt(" #n ")" ::: "memory")
; #define PG8_BAR __builtin_amdgcn_s_barrier()
; #define PG8_SCHED __builtin_amdgcn_sched_barrier(0)
; template <class Epi, class Sched, bool ALIGN_EPI = false, bool SP2 = false>
; __device__ __forceinline__ void gemm_phase(PG8_LAS unsigned char* lds, const Gemm g, const Sched& S, const Epi& E) {
;     ...
;         for (int t = 0; t < nt; t += 2) {
;             const bool last = (t == nt - 2);
;             const char* a1 = cA + (long)(t + 1) * kstepA;
;             const char* a2 = last ? nA : cA + (long)(t + 2) * kstepA; const char* b2 = last ? nB : cB + (long)(t + 2) * kstep;
;     ...
;             PG8_LDA(At, 1, 1); PG8_STAGE(PG8_SB(1, 0), b3, voffB); PG8_STAGE(PG8_SB(1, 1), b3 + hstepB, voffB); PG8_STAGE(PG8_SA(1, 0), a3, voffA);
;             PG8_WAIT_V(8); PG8_WAIT_L(0); PG8_BAR; PG8_MMA(1, 0, At, B0); PG8_MMA(1, 1, At, B1); PG8_BAR; PG8_SCHED;
	s_add_i32 s50, s69, s17
	v_lshl_add_u64 v[176:177], v[176:177], 0, s[24:25]
	s_mov_b32 m0, s50
	ds_read_b128 v[180:183], v217 offset:49152
	ds_read_b128 v[186:189], v217 offset:50176
	ds_read_b128 v[192:195], v217 offset:51200
	ds_read_b128 v[204:207], v217 offset:52224
	ds_read_b128 v[208:211], v217 offset:53248
	ds_read_b128 v[212:215], v217 offset:54272
	ds_read_b128 v[218:221], v217 offset:55296
	ds_read_b128 v[222:225], v217 offset:56320
	global_load_lds_dwordx4 v[176:177], off
	s_add_i32 m0, s50, 0x2000
	s_add_u32 s48, s48, 0x40080
	v_lshl_add_u64 v[176:177], v[196:197], 0, s[24:25]
	s_addc_u32 s49, s49, 0
	s_add_i32 s50, s70, s17
	global_load_lds_dwordx4 v[176:177], off
	v_lshl_add_u64 v[176:177], s[48:49], 0, v[164:165]
	s_mov_b32 m0, s50
	s_nop 0
	global_load_lds_dwordx4 v[176:177], off
	v_lshl_add_u64 v[176:177], s[48:49], 0, v[160:161]
	s_add_i32 m0, s50, 0x2000
	s_nop 0
	global_load_lds_dwordx4 v[176:177], off
	v_lshl_add_u64 v[176:177], v[200:201], 0, s[24:25]
	s_mov_b32 m0, s56
	s_nop 0
	global_load_lds_dwordx4 v[176:177], off
	v_lshl_add_u64 v[176:177], v[226:227], 0, s[24:25]
	s_mov_b32 m0, s57
	s_nop 0
	global_load_lds_dwordx4 v[176:177], off
	s_waitcnt vmcnt(8)
	s_waitcnt lgkmcnt(0)
	s_barrier
	s_setprio 1
	s_waitcnt lgkmcnt(0)
	v_mfma_f32_16x16x32_bf16 v[56:59], v[112:115], v[180:183], v[56:59]
	v_mfma_f32_16x16x32_bf16 v[48:51], v[128:131], v[180:183], v[48:51]
	v_mfma_f32_16x16x32_bf16 v[40:43], v[112:115], v[192:195], v[40:43]
	v_mfma_f32_16x16x32_bf16 v[32:35], v[128:131], v[192:195], v[32:35]
	v_mfma_f32_16x16x32_bf16 v[24:27], v[112:115], v[208:211], v[24:27]
	v_mfma_f32_16x16x32_bf16 v[16:19], v[128:131], v[208:211], v[16:19]
	v_mfma_f32_16x16x32_bf16 v[8:11], v[112:115], v[218:221], v[8:11]
	v_mfma_f32_16x16x32_bf16 v[4:7], v[128:131], v[218:221], v[4:7]
	v_mfma_f32_16x16x32_bf16 v[56:59], v[116:119], v[186:189], v[56:59]
	v_mfma_f32_16x16x32_bf16 v[48:51], v[132:135], v[186:189], v[48:51]
	v_mfma_f32_16x16x32_bf16 v[40:43], v[116:119], v[204:207], v[40:43]
	v_mfma_f32_16x16x32_bf16 v[32:35], v[132:135], v[204:207], v[32:35]
	v_mfma_f32_16x16x32_bf16 v[24:27], v[116:119], v[212:215], v[24:27]
	v_mfma_f32_16x16x32_bf16 v[16:19], v[132:135], v[212:215], v[16:19]
	v_mfma_f32_16x16x32_bf16 v[8:11], v[116:119], v[222:225], v[8:11]
	v_mfma_f32_16x16x32_bf16 v[4:7], v[132:135], v[222:225], v[4:7]
	s_setprio 0
	s_setprio 1
	v_mfma_f32_16x16x32_bf16 v[60:63], v[136:139], v[180:183], v[60:63]
	v_mfma_f32_16x16x32_bf16 v[52:55], v[152:155], v[180:183], v[52:55]
	v_mfma_f32_16x16x32_bf16 v[44:47], v[136:139], v[192:195], v[44:47]
	v_mfma_f32_16x16x32_bf16 v[36:39], v[152:155], v[192:195], v[36:39]
	v_mfma_f32_16x16x32_bf16 v[28:31], v[136:139], v[208:211], v[28:31]
	v_mfma_f32_16x16x32_bf16 v[20:23], v[152:155], v[208:211], v[20:23]
	v_mfma_f32_16x16x32_bf16 v[12:15], v[136:139], v[218:221], v[12:15]
	v_mfma_f32_16x16x32_bf16 v[0:3], v[152:155], v[218:221], v[0:3]
	v_mfma_f32_16x16x32_bf16 v[60:63], v[148:151], v[186:189], v[60:63]
	v_mfma_f32_16x16x32_bf16 v[52:55], v[156:159], v[186:189], v[52:55]
	v_mfma_f32_16x16x32_bf16 v[44:47], v[148:151], v[204:207], v[44:47]
	v_mfma_f32_16x16x32_bf16 v[36:39], v[156:159], v[204:207], v[36:39]
	v_mfma_f32_16x16x32_bf16 v[28:31], v[148:151], v[212:215], v[28:31]
	v_mfma_f32_16x16x32_bf16 v[20:23], v[156:159], v[212:215], v[20:23]
	v_mfma_f32_16x16x32_bf16 v[12:15], v[148:151], v[222:225], v[12:15]
	v_mfma_f32_16x16x32_bf16 v[0:3], v[156:159], v[222:225], v[0:3]
	s_setprio 0
	s_barrier
	s_add_u32 s46, s46, 0x100
	s_addc_u32 s47, s47, 0
	s_add_u32 s66, s66, 0x100
	s_addc_u32 s67, s67, 0
	s_cmp_ge_i32 s68, s53
	s_mov_b32 s48, s68
	s_cbranch_scc0 .LBB0_1257

; __device__ __forceinline__ void load_row_stats(const float* sp, int row0, RowStats& r) {
; #pragma unroll
;     for (int ai = 0; ai < 2; ++ai) { asm volatile("" ::: "memory");
; #pragma unroll
;         for (int m = 0; m < 4; ++m) { const float* p = sp + (size_t)(row0 + ai * HALF + m * 16) * 8; const f32x4 a = *(const f32x4*)p, b = *(const f32x4*)(p + 4);
;             const float s1 = (a[0] + a[2]) + (b[0] + b[2]), s2 = (a[1] + a[3]) + (b[1] + b[3]); const float mu = s1 * (1.f / 1024.f); const float var = s2 * (1.f / 1024.f) - mu * mu;
;             r.mu[ai][m] = mu; r.rs[ai][m] = __builtin_amdgcn_rsqf(__builtin_fmaxf(var, 0.f) + 1e-5f); } }
.LBB0_1260:
	s_lshl_b32 s35, s44, 8
	v_mov_b32_e32 v112, v185
	v_mov_b32_e32 v113, v179
	s_add_i32 s35, s35, s54
	s_andn2_b64 vcc, exec, s[38:39]
	v_add_u32_e32 v192, s35, v113
	v_ashrrev_i32_e32 v193, 31, v192
	s_cselect_b32 s99, 1, 0
	v_readfirstlane_b32 s98, v254
	v_and_b32_e32 v114, 0xffffff00, v192
	s_nop 0
	s_cmpk_lt_u32 s98, 0x100
	s_cbranch_scc0 .Lrs2_skip
	v_pk_add_f32 v[114:115], v[246:247], v[248:249]
	v_pk_add_f32 v[118:119], v[250:251], v[252:253]
	s_nop 0
	v_pk_add_f32 v[114:115], v[118:119], v[114:115]
	s_nop 0
	v_pk_mul_f32 v[114:115], v[114:115], s[30:31] op_sel_hi:[1,0]
	v_lshlrev_b32_e32 v116, 3, v254
	v_add_u32_e32 v116, 0x22400, v116
	ds_write_b64 v116, v[114:115]

; template <class Epi, class Sched, bool ALIGN_EPI = false, bool SP2 = false>
; __device__ __forceinline__ void gemm_phase(PG8_LAS unsigned char* lds, const Gemm g, const Sched& S, const Epi& E) {
;     ...
;         const char* nA = has_next ? (const char*)g.A + (size_t)nxt.pm * tstepA : cA; const char* nB = has_next ? (const char*)g.Bt + (size_t)nxt.pn * tstepB : cB;
;         for (int t = 0; t < nt; t += 2) {
;             const bool last = (t == nt - 2);
;             const char* a1 = cA + (long)(t + 1) * kstepA;
;             const char* a2 = last ? nA : cA + (long)(t + 2) * kstepA; const char* b2 = last ? nB : cB + (long)(t + 2) * kstep;
;     ...
; #pragma unroll
;         for (int a = 0; a < 2; ++a)
; #pragma unroll
;             for (int b = 0; b < 2; ++b)
; #pragma unroll
;                 for (int m = 0; m < 4; ++m)
; #pragma unroll
;                     for (int n = 0; n < 2; ++n) acc[a][b][m][n] = (f32x4){0.f, 0.f, 0.f, 0.f};
;         cur = nxt; cA = nA; cB = nB; ++ui;
.LBB0_1693:
	s_ashr_i32 s47, s46, 31
	s_lshl_b64 s[20:21], s[46:47], 19
	s_add_u32 s48, s8, s20
	s_addc_u32 s49, s9, s21
	s_ashr_i32 s45, s44, 31
	s_lshl_b64 s[20:21], s[44:45], 19
	s_add_u32 s50, s55, s20
	v_mov_b32_e32 v135, 0
	s_addc_u32 s51, s56, s21
	s_andn2_b64 vcc, exec, s[34:35]
	v_mov_b32_e32 v134, v135
	v_mov_b32_e32 v133, v135
	v_mov_b32_e32 v132, v135
	v_mov_b32_e32 v131, v135
	v_mov_b32_e32 v130, v135
	v_mov_b32_e32 v129, v135
	v_mov_b32_e32 v128, v135
	v_mov_b32_e32 v119, v135
	v_mov_b32_e32 v118, v135
	v_mov_b32_e32 v117, v135
	v_mov_b32_e32 v116, v135
	v_mov_b32_e32 v115, v135
	v_mov_b32_e32 v114, v135
	v_mov_b32_e32 v113, v135
	v_mov_b32_e32 v112, v135
	v_mov_b32_e32 v111, v135
	v_mov_b32_e32 v110, v135
	v_mov_b32_e32 v109, v135
	v_mov_b32_e32 v108, v135
	v_mov_b32_e32 v107, v135
	v_mov_b32_e32 v106, v135
	v_mov_b32_e32 v105, v135
	v_mov_b32_e32 v104, v135
	v_mov_b32_e32 v103, v135
	v_mov_b32_e32 v102, v135
	v_mov_b32_e32 v101, v135
	v_mov_b32_e32 v100, v135
	v_mov_b32_e32 v99, v135
	v_mov_b32_e32 v98, v135
	v_mov_b32_e32 v97, v135
	v_mov_b32_e32 v96, v135
	v_mov_b32_e32 v63, v135
	v_mov_b32_e32 v62, v135
	v_mov_b32_e32 v61, v135
	v_mov_b32_e32 v60, v135
	v_mov_b32_e32 v59, v135
	v_mov_b32_e32 v58, v135
	v_mov_b32_e32 v57, v135
	v_mov_b32_e32 v56, v135
	v_mov_b32_e32 v55, v135
	v_mov_b32_e32 v54, v135
	v_mov_b32_e32 v53, v135
	v_mov_b32_e32 v52, v135
	v_mov_b32_e32 v51, v135
	v_mov_b32_e32 v50, v135
	v_mov_b32_e32 v49, v135
	v_mov_b32_e32 v48, v135
	v_mov_b32_e32 v47, v135
	v_mov_b32_e32 v46, v135
	v_mov_b32_e32 v45, v135
	v_mov_b32_e32 v44, v135
	v_mov_b32_e32 v43, v135
	v_mov_b32_e32 v42, v135
	v_mov_b32_e32 v41, v135
	v_mov_b32_e32 v40, v135
	v_mov_b32_e32 v39, v135
	v_mov_b32_e32 v38, v135
	v_mov_b32_e32 v37, v135
	v_mov_b32_e32 v36, v135
	v_mov_b32_e32 v35, v135
	v_mov_b32_e32 v34, v135
	v_mov_b32_e32 v33, v135
	v_mov_b32_e32 v32, v135
	v_mov_b32_e32 v95, v135
	v_mov_b32_e32 v94, v135
	v_mov_b32_e32 v93, v135
	v_mov_b32_e32 v92, v135
	v_mov_b32_e32 v91, v135
	v_mov_b32_e32 v90, v135
	v_mov_b32_e32 v89, v135
	v_mov_b32_e32 v88, v135
	v_mov_b32_e32 v87, v135
	v_mov_b32_e32 v86, v135
	v_mov_b32_e32 v85, v135
	v_mov_b32_e32 v84, v135
	v_mov_b32_e32 v83, v135
	v_mov_b32_e32 v82, v135
	v_mov_b32_e32 v81, v135
	v_mov_b32_e32 v80, v135
	v_mov_b32_e32 v79, v135
	v_mov_b32_e32 v78, v135
	v_mov_b32_e32 v77, v135
	v_mov_b32_e32 v76, v135
	v_mov_b32_e32 v75, v135
	v_mov_b32_e32 v74, v135
	v_mov_b32_e32 v73, v135
	v_mov_b32_e32 v72, v135
	v_mov_b32_e32 v71, v135
	v_mov_b32_e32 v70, v135
	v_mov_b32_e32 v69, v135
	v_mov_b32_e32 v68, v135
	v_mov_b32_e32 v67, v135
	v_mov_b32_e32 v66, v135
	v_mov_b32_e32 v65, v135
	v_mov_b32_e32 v64, v135
	v_mov_b32_e32 v31, v135
	v_mov_b32_e32 v30, v135
	v_mov_b32_e32 v29, v135
	v_mov_b32_e32 v28, v135
	v_mov_b32_e32 v27, v135
	v_mov_b32_e32 v26, v135
	v_mov_b32_e32 v25, v135
	v_mov_b32_e32 v24, v135
	v_mov_b32_e32 v23, v135
	v_mov_b32_e32 v22, v135
	v_mov_b32_e32 v21, v135
	v_mov_b32_e32 v20, v135
	v_mov_b32_e32 v19, v135
	v_mov_b32_e32 v18, v135
	v_mov_b32_e32 v17, v135
	v_mov_b32_e32 v16, v135
	v_mov_b32_e32 v15, v135
	v_mov_b32_e32 v14, v135
	v_mov_b32_e32 v13, v135
	v_mov_b32_e32 v12, v135
	v_mov_b32_e32 v11, v135
	v_mov_b32_e32 v10, v135
	v_mov_b32_e32 v9, v135
	v_mov_b32_e32 v8, v135
	v_mov_b32_e32 v7, v135
	v_mov_b32_e32 v6, v135
	v_mov_b32_e32 v5, v135
	v_mov_b32_e32 v4, v135
	v_mov_b32_e32 v3, v135
	v_mov_b32_e32 v2, v135
	v_mov_b32_e32 v1, v135
	v_mov_b32_e32 v0, v135
	s_cbranch_vccnz .LBB0_1696
	s_and_b64 s[20:21], s[38:39], exec
	s_cselect_b32 s11, s49, s13
	s_cselect_b32 s19, s48, s12
	s_cselect_b32 s20, s51, s37
	s_cselect_b32 s21, s50, s36
	s_add_u32 s12, s12, 0x40080
	s_addc_u32 s13, s13, 0
	s_add_u32 s45, s36, 0x100
	v_mov_b32_e32 v0, 0
	s_addc_u32 s47, s37, 0
	s_mov_b32 s36, 0
	v_mov_b32_e32 v1, v0
	v_mov_b32_e32 v2, v0
	v_mov_b32_e32 v3, v0
	v_mov_b32_e32 v4, v0
	v_mov_b32_e32 v5, v0
	v_mov_b32_e32 v6, v0
	v_mov_b32_e32 v7, v0
	v_mov_b32_e32 v8, v0
	v_mov_b32_e32 v9, v0
	v_mov_b32_e32 v10, v0
	v_mov_b32_e32 v11, v0
	v_mov_b32_e32 v12, v0
	v_mov_b32_e32 v13, v0
	v_mov_b32_e32 v14, v0
	v_mov_b32_e32 v15, v0
	v_mov_b32_e32 v16, v0
	v_mov_b32_e32 v17, v0
	v_mov_b32_e32 v18, v0
	v_mov_b32_e32 v19, v0
	v_mov_b32_e32 v20, v0
	v_mov_b32_e32 v21, v0
	v_mov_b32_e32 v22, v0
	v_mov_b32_e32 v23, v0
	v_mov_b32_e32 v24, v0
	v_mov_b32_e32 v25, v0
	v_mov_b32_e32 v26, v0
	v_mov_b32_e32 v27, v0
	v_mov_b32_e32 v28, v0
	v_mov_b32_e32 v29, v0
	v_mov_b32_e32 v30, v0
	v_mov_b32_e32 v31, v0
	v_mov_b32_e32 v64, v0
	v_mov_b32_e32 v65, v0
	v_mov_b32_e32 v66, v0
	v_mov_b32_e32 v67, v0
	v_mov_b32_e32 v68, v0
	v_mov_b32_e32 v69, v0
	v_mov_b32_e32 v70, v0
	v_mov_b32_e32 v71, v0
	v_mov_b32_e32 v72, v0
	v_mov_b32_e32 v73, v0
	v_mov_b32_e32 v74, v0
	v_mov_b32_e32 v75, v0
	v_mov_b32_e32 v76, v0
	v_mov_b32_e32 v77, v0
	v_mov_b32_e32 v78, v0
	v_mov_b32_e32 v79, v0
	v_mov_b32_e32 v80, v0
	v_mov_b32_e32 v81, v0
	v_mov_b32_e32 v82, v0
	v_mov_b32_e32 v83, v0
	v_mov_b32_e32 v84, v0
	v_mov_b32_e32 v85, v0
	v_mov_b32_e32 v86, v0
	v_mov_b32_e32 v87, v0
	v_mov_b32_e32 v88, v0
	v_mov_b32_e32 v89, v0
	v_mov_b32_e32 v90, v0
	v_mov_b32_e32 v91, v0
	v_mov_b32_e32 v92, v0
	v_mov_b32_e32 v93, v0
	v_mov_b32_e32 v94, v0
	v_mov_b32_e32 v95, v0
	v_mov_b32_e32 v32, v0
	v_mov_b32_e32 v33, v0
	v_mov_b32_e32 v34, v0
	v_mov_b32_e32 v35, v0
	v_mov_b32_e32 v36, v0
	v_mov_b32_e32 v37, v0
	v_mov_b32_e32 v38, v0
	v_mov_b32_e32 v39, v0
	v_mov_b32_e32 v40, v0
	v_mov_b32_e32 v41, v0
	v_mov_b32_e32 v42, v0
	v_mov_b32_e32 v43, v0
	v_mov_b32_e32 v44, v0
	v_mov_b32_e32 v45, v0
	v_mov_b32_e32 v46, v0
	v_mov_b32_e32 v47, v0
	v_mov_b32_e32 v48, v0
	v_mov_b32_e32 v49, v0
	v_mov_b32_e32 v50, v0
	v_mov_b32_e32 v51, v0
	v_mov_b32_e32 v52, v0
	v_mov_b32_e32 v53, v0
	v_mov_b32_e32 v54, v0
	v_mov_b32_e32 v55, v0
	v_mov_b32_e32 v56, v0
	v_mov_b32_e32 v57, v0
	v_mov_b32_e32 v58, v0
	v_mov_b32_e32 v59, v0
	v_mov_b32_e32 v60, v0
	v_mov_b32_e32 v61, v0
	v_mov_b32_e32 v62, v0
	v_mov_b32_e32 v63, v0
	v_mov_b32_e32 v96, v0
	v_mov_b32_e32 v97, v0
	v_mov_b32_e32 v98, v0
	v_mov_b32_e32 v99, v0
	v_mov_b32_e32 v100, v0
	v_mov_b32_e32 v101, v0
	v_mov_b32_e32 v102, v0
	v_mov_b32_e32 v103, v0
	v_mov_b32_e32 v104, v0
	v_mov_b32_e32 v105, v0
	v_mov_b32_e32 v106, v0
	v_mov_b32_e32 v107, v0
	v_mov_b32_e32 v108, v0
	v_mov_b32_e32 v109, v0
	v_mov_b32_e32 v110, v0
	v_mov_b32_e32 v111, v0
	v_mov_b32_e32 v112, v0
	v_mov_b32_e32 v113, v0
	v_mov_b32_e32 v114, v0
	v_mov_b32_e32 v115, v0
	v_mov_b32_e32 v116, v0
	v_mov_b32_e32 v117, v0
	v_mov_b32_e32 v118, v0
	v_mov_b32_e32 v119, v0
	v_mov_b32_e32 v128, v0
	v_mov_b32_e32 v129, v0
	v_mov_b32_e32 v130, v0
	v_mov_b32_e32 v131, v0
	v_mov_b32_e32 v132, v0
	v_mov_b32_e32 v133, v0
	v_mov_b32_e32 v134, v0
	v_mov_b32_e32 v135, v0
	v_readfirstlane_b32 s98, v254
	s_lshl_b32 s99, s10, 8
	s_nop 0
	s_cmpk_lt_u32 s98, 0x100
	s_cbranch_scc0 .Lrs5_nopre
; #define PG8_STAGE(bufoff, gbase, voff) do { _Pragma("unroll") for (int _i = 0; _i < 2; ++_i) \
;         __builtin_amdgcn_global_load_lds((const unsigned*)((const char*)(gbase) + (voff)[_i]), (PG8_LAS unsigned*)(lds + (bufoff) + ldsw + _i * 8192), 16, 0, 0); } while (0)
; #define PG8_LDA(dst, b, h) do { _Pragma("unroll") for (int m = 0; m < 4; ++m) _Pragma("unroll") for (int k = 0; k < 2; ++k) dst[m][k] = *(const PG8_LAS bf16x8*)(lds + PG8_SA(b, h) + aoff + m * 2048 + k * 1024); } while (0)
; #define PG8_LDB(dst, b, h) do { _Pragma("unroll") for (int n = 0; n < 2; ++n) _Pragma("unroll") for (int k = 0; k < 2; ++k) dst[n][k] = *(const PG8_LAS bf16x8*)(lds + PG8_SB(b, h) + boff + n * 2048 + k * 1024); } while (0)
; #define PG8_MMA(ai, bj, At, Bt) do { __builtin_amdgcn_s_setprio(1); _Pragma("unroll") for (int m = 0; m < 4; ++m) _Pragma("unroll") for (int n = 0; n < 2; ++n) _Pragma("unroll") for (int k = 0; k < 2; ++k) \
;         acc[ai][bj][m][n] = __builtin_amdgcn_mfma_f32_16x16x32_bf16(Bt[n][k], At[m][k], acc[ai][bj][m][n], 0, 0, 0); __builtin_amdgcn_s_setprio(0); } while (0)
; #define PG8_WAIT_V(n) asm volatile("s_waitcnt vmcnt(" #n ")" ::: "memory")
; #define PG8_WAIT_L(n) asm volatile("s_waitcnt lgkmcnt(" #n ")" ::: "memory")
; #define PG8_BAR __builtin_amdgcn_s_barrier()
; #define PG8_SCHED __builtin_amdgcn_sched_barrier(0)
; __device__ __forceinline__ void load_row_stats(const float* sp, int row0, RowStats& r) {
;     ...
;         for (int m = 0; m < 4; ++m) { const float* p = sp + (size_t)(row0 + ai * HALF + m * 16) * 8; const f32x4 a = *(const f32x4*)p, b = *(const f32x4*)(p + 4);
; template <class Epi, class Sched, bool ALIGN_EPI = false, bool SP2 = false>
; __device__ __forceinline__ void gemm_phase(PG8_LAS unsigned char* lds, const Gemm g, const Sched& S, const Epi& E) {
;     ...
;             PG8_LDB(B0, 0, 0); PG8_LDB(B1, 0, 1); PG8_SCHED; PG8_LDA(At, 0, 0); PG8_STAGE(PG8_SA(1, 1), a1 + hstepA, voffA);
;             PG8_WAIT_V(8); PG8_WAIT_L(0); PG8_BAR; PG8_MMA(0, 0, At, B0); PG8_MMA(0, 1, At, B1); PG8_BAR; PG8_SCHED;
;             PG8_LDA(At, 0, 1); PG8_STAGE(PG8_SB(0, 0), b2, voffB); PG8_STAGE(PG8_SB(0, 1), b2 + hstepB, voffB); PG8_STAGE(PG8_SA(0, 0), a2, voffA);
;             PG8_WAIT_V(8); PG8_WAIT_L(0); PG8_BAR; PG8_MMA(1, 0, At, B0); PG8_MMA(1, 1, At, B1); PG8_BAR; PG8_SCHED;
	v_add_u32_e32 v244, s99, v254
	v_mov_b32_e32 v245, 0
	v_lshlrev_b64 v[244:245], 5, v[244:245]
	v_lshl_add_u64 v[244:245], s[24:25], 0, v[244:245]
	global_load_dwordx4 v[246:249], v[244:245], off offset:16
	global_load_dwordx4 v[250:253], v[244:245], off
.Lrs5_nopre:
.LBB0_1695:
	ds_read_b128 v[120:123], v183
	ds_read_b128 v[124:127], v183 offset:1024
	ds_read_b128 v[136:139], v183 offset:2048
	ds_read_b128 v[140:143], v183 offset:3072
	ds_read_b128 v[144:147], v187
	ds_read_b128 v[148:151], v187 offset:1024
	ds_read_b128 v[192:195], v187 offset:2048
	ds_read_b128 v[196:199], v187 offset:3072
	s_add_i32 s67, s36, 2
	s_add_u32 s37, s12, 0xfffc0080
	s_addc_u32 s52, s13, -1
	s_cmp_eq_u32 s63, s36
	s_cselect_b32 s36, s21, s45
	s_cselect_b32 s53, s11, s52
	s_cselect_b32 s52, s19, s37
	s_cselect_b32 s37, s20, s47
	v_lshl_add_u64 v[168:169], s[12:13], 0, v[160:161]
	s_add_i32 m0, s58, 0xc000
	ds_read_b128 v[200:203], v191
	ds_read_b128 v[204:207], v191 offset:1024
	ds_read_b128 v[208:211], v191 offset:2048
	ds_read_b128 v[212:215], v191 offset:3072
	ds_read_b128 v[216:219], v191 offset:4096
	ds_read_b128 v[220:223], v191 offset:5120
	ds_read_b128 v[224:227], v191 offset:6144
	ds_read_b128 v[228:231], v191 offset:7168
	global_load_lds_dwordx4 v[168:169], off
	v_lshl_add_u64 v[168:169], s[12:13], 0, v[162:163]
	s_add_i32 m0, s58, 0xe000
	s_nop 0
	global_load_lds_dwordx4 v[168:169], off
	s_waitcnt vmcnt(8)
	s_waitcnt lgkmcnt(0)
	s_barrier
	s_setprio 1
	s_waitcnt lgkmcnt(0)
	v_mfma_f32_16x16x32_bf16 v[132:135], v[120:123], v[200:203], v[132:135]
	v_mfma_f32_16x16x32_bf16 v[128:131], v[136:139], v[200:203], v[128:131]
	v_mfma_f32_16x16x32_bf16 v[116:119], v[120:123], v[208:211], v[116:119]
	v_mfma_f32_16x16x32_bf16 v[112:115], v[136:139], v[208:211], v[112:115]
	v_mfma_f32_16x16x32_bf16 v[108:111], v[120:123], v[216:219], v[108:111]
	v_mfma_f32_16x16x32_bf16 v[104:107], v[136:139], v[216:219], v[104:107]
	v_mfma_f32_16x16x32_bf16 v[100:103], v[120:123], v[224:227], v[100:103]
	v_mfma_f32_16x16x32_bf16 v[96:99], v[136:139], v[224:227], v[96:99]
	v_mfma_f32_16x16x32_bf16 v[132:135], v[124:127], v[204:207], v[132:135]
	v_mfma_f32_16x16x32_bf16 v[128:131], v[140:143], v[204:207], v[128:131]
	v_mfma_f32_16x16x32_bf16 v[116:119], v[124:127], v[212:215], v[116:119]
	v_mfma_f32_16x16x32_bf16 v[112:115], v[140:143], v[212:215], v[112:115]
	v_mfma_f32_16x16x32_bf16 v[108:111], v[124:127], v[220:223], v[108:111]
	v_mfma_f32_16x16x32_bf16 v[104:107], v[140:143], v[220:223], v[104:107]
	v_mfma_f32_16x16x32_bf16 v[100:103], v[124:127], v[228:231], v[100:103]
	v_mfma_f32_16x16x32_bf16 v[96:99], v[140:143], v[228:231], v[96:99]
	s_setprio 0
	s_setprio 1
	v_mfma_f32_16x16x32_bf16 v[60:63], v[144:147], v[200:203], v[60:63]
	v_mfma_f32_16x16x32_bf16 v[56:59], v[192:195], v[200:203], v[56:59]
	v_mfma_f32_16x16x32_bf16 v[52:55], v[144:147], v[208:211], v[52:55]
	v_mfma_f32_16x16x32_bf16 v[48:51], v[192:195], v[208:211], v[48:51]
	v_mfma_f32_16x16x32_bf16 v[44:47], v[144:147], v[216:219], v[44:47]
	v_mfma_f32_16x16x32_bf16 v[40:43], v[192:195], v[216:219], v[40:43]
	v_mfma_f32_16x16x32_bf16 v[36:39], v[144:147], v[224:227], v[36:39]
	v_mfma_f32_16x16x32_bf16 v[32:35], v[192:195], v[224:227], v[32:35]
	v_mfma_f32_16x16x32_bf16 v[60:63], v[148:151], v[204:207], v[60:63]
	v_mfma_f32_16x16x32_bf16 v[56:59], v[196:199], v[204:207], v[56:59]
	v_mfma_f32_16x16x32_bf16 v[52:55], v[148:151], v[212:215], v[52:55]
	v_mfma_f32_16x16x32_bf16 v[48:51], v[196:199], v[212:215], v[48:51]
	v_mfma_f32_16x16x32_bf16 v[44:47], v[148:151], v[220:223], v[44:47]
	v_mfma_f32_16x16x32_bf16 v[40:43], v[196:199], v[220:223], v[40:43]
	v_mfma_f32_16x16x32_bf16 v[36:39], v[148:151], v[228:231], v[36:39]
	v_mfma_f32_16x16x32_bf16 v[32:35], v[196:199], v[228:231], v[32:35]
	s_setprio 0
	s_barrier
	s_add_i32 s68, s65, s57
	v_lshl_add_u64 v[168:169], s[36:37], 0, v[154:155]
	s_mov_b32 m0, s68
	ds_read_b128 v[200:203], v191 offset:16384
	ds_read_b128 v[204:207], v191 offset:17408
	ds_read_b128 v[208:211], v191 offset:18432
	ds_read_b128 v[212:215], v191 offset:19456
	ds_read_b128 v[216:219], v191 offset:20480
	ds_read_b128 v[220:223], v191 offset:21504
	ds_read_b128 v[224:227], v191 offset:22528
	ds_read_b128 v[228:231], v191 offset:23552
	global_load_lds_dwordx4 v[168:169], off
	s_add_i32 m0, s68, 0x2000
	s_add_u32 s68, s36, 0x40000
	v_lshl_add_u64 v[172:173], s[36:37], 0, v[158:159]
	s_addc_u32 s69, s37, 0
	s_add_i32 s70, s66, s57
	global_load_lds_dwordx4 v[172:173], off
	v_lshl_add_u64 v[176:177], s[68:69], 0, v[154:155]
	s_mov_b32 m0, s70
	v_lshl_add_u64 v[180:181], s[52:53], 0, v[156:157]
	global_load_lds_dwordx4 v[176:177], off
	v_lshl_add_u64 v[176:177], s[68:69], 0, v[158:159]
	s_add_i32 m0, s70, 0x2000
	s_nop 0
	global_load_lds_dwordx4 v[176:177], off
	v_lshl_add_u64 v[176:177], s[52:53], 0, v[152:153]
	s_mov_b32 m0, s58
	s_nop 0
	global_load_lds_dwordx4 v[176:177], off
	s_mov_b32 m0, s33
	s_nop 0
	global_load_lds_dwordx4 v[180:181], off
	s_waitcnt vmcnt(8)
	s_waitcnt lgkmcnt(0)
	s_barrier
; #define PG8_STAGE(bufoff, gbase, voff) do { _Pragma("unroll") for (int _i = 0; _i < 2; ++_i) \
;         __builtin_amdgcn_global_load_lds((const unsigned*)((const char*)(gbase) + (voff)[_i]), (PG8_LAS unsigned*)(lds + (bufoff) + ldsw + _i * 8192), 16, 0, 0); } while (0)
; #define PG8_LDA(dst, b, h) do { _Pragma("unroll") for (int m = 0; m < 4; ++m) _Pragma("unroll") for (int k = 0; k < 2; ++k) dst[m][k] = *(const PG8_LAS bf16x8*)(lds + PG8_SA(b, h) + aoff + m * 2048 + k * 1024); } while (0)
; #define PG8_LDB(dst, b, h) do { _Pragma("unroll") for (int n = 0; n < 2; ++n) _Pragma("unroll") for (int k = 0; k < 2; ++k) dst[n][k] = *(const PG8_LAS bf16x8*)(lds + PG8_SB(b, h) + boff + n * 2048 + k * 1024); } while (0)
; #define PG8_MMA(ai, bj, At, Bt) do { __builtin_amdgcn_s_setprio(1); _Pragma("unroll") for (int m = 0; m < 4; ++m) _Pragma("unroll") for (int n = 0; n < 2; ++n) _Pragma("unroll") for (int k = 0; k < 2; ++k) \
;         acc[ai][bj][m][n] = __builtin_amdgcn_mfma_f32_16x16x32_bf16(Bt[n][k], At[m][k], acc[ai][bj][m][n], 0, 0, 0); __builtin_amdgcn_s_setprio(0); } while (0)
; #define PG8_WAIT_V(n) asm volatile("s_waitcnt vmcnt(" #n ")" ::: "memory")
; #define PG8_WAIT_L(n) asm volatile("s_waitcnt lgkmcnt(" #n ")" ::: "memory")
; #define PG8_BAR __builtin_amdgcn_s_barrier()
; #define PG8_SCHED __builtin_amdgcn_sched_barrier(0)
; template <class Epi, class Sched, bool ALIGN_EPI = false, bool SP2 = false>
; __device__ __forceinline__ void gemm_phase(PG8_LAS unsigned char* lds, const Gemm g, const Sched& S, const Epi& E) {
;     ...
;             PG8_WAIT_V(8); PG8_WAIT_L(0); PG8_BAR; PG8_MMA(1, 0, At, B0); PG8_MMA(1, 1, At, B1); PG8_BAR; PG8_SCHED;
;             PG8_LDB(B0, 1, 0); PG8_LDB(B1, 1, 1); PG8_SCHED; PG8_LDA(At, 1, 0); PG8_STAGE(PG8_SA(0, 1), a2 + hstepA, voffA);
;             PG8_WAIT_V(8); PG8_WAIT_L(0); PG8_BAR; PG8_MMA(0, 0, At, B0); PG8_MMA(0, 1, At, B1); PG8_BAR; PG8_SCHED;
	s_setprio 1
	s_waitcnt lgkmcnt(0)
	v_mfma_f32_16x16x32_bf16 v[92:95], v[120:123], v[200:203], v[92:95]
	v_mfma_f32_16x16x32_bf16 v[88:91], v[136:139], v[200:203], v[88:91]
	v_mfma_f32_16x16x32_bf16 v[84:87], v[120:123], v[208:211], v[84:87]
	v_mfma_f32_16x16x32_bf16 v[80:83], v[136:139], v[208:211], v[80:83]
	v_mfma_f32_16x16x32_bf16 v[76:79], v[120:123], v[216:219], v[76:79]
	v_mfma_f32_16x16x32_bf16 v[72:75], v[136:139], v[216:219], v[72:75]
	v_mfma_f32_16x16x32_bf16 v[68:71], v[120:123], v[224:227], v[68:71]
	v_mfma_f32_16x16x32_bf16 v[64:67], v[136:139], v[224:227], v[64:67]
	v_mfma_f32_16x16x32_bf16 v[92:95], v[124:127], v[204:207], v[92:95]
	v_mfma_f32_16x16x32_bf16 v[88:91], v[140:143], v[204:207], v[88:91]
	v_mfma_f32_16x16x32_bf16 v[84:87], v[124:127], v[212:215], v[84:87]
	v_mfma_f32_16x16x32_bf16 v[80:83], v[140:143], v[212:215], v[80:83]
	v_mfma_f32_16x16x32_bf16 v[76:79], v[124:127], v[220:223], v[76:79]
	v_mfma_f32_16x16x32_bf16 v[72:75], v[140:143], v[220:223], v[72:75]
	v_mfma_f32_16x16x32_bf16 v[68:71], v[124:127], v[228:231], v[68:71]
	v_mfma_f32_16x16x32_bf16 v[64:67], v[140:143], v[228:231], v[64:67]
	s_setprio 0
	s_setprio 1
	v_mfma_f32_16x16x32_bf16 v[28:31], v[144:147], v[200:203], v[28:31]
	v_mfma_f32_16x16x32_bf16 v[24:27], v[192:195], v[200:203], v[24:27]
	v_mfma_f32_16x16x32_bf16 v[20:23], v[144:147], v[208:211], v[20:23]
	v_mfma_f32_16x16x32_bf16 v[16:19], v[192:195], v[208:211], v[16:19]
	v_mfma_f32_16x16x32_bf16 v[12:15], v[144:147], v[216:219], v[12:15]
	v_mfma_f32_16x16x32_bf16 v[8:11], v[192:195], v[216:219], v[8:11]
	v_mfma_f32_16x16x32_bf16 v[4:7], v[144:147], v[224:227], v[4:7]
	v_mfma_f32_16x16x32_bf16 v[0:3], v[192:195], v[224:227], v[0:3]
	v_mfma_f32_16x16x32_bf16 v[28:31], v[148:151], v[204:207], v[28:31]
	v_mfma_f32_16x16x32_bf16 v[24:27], v[196:199], v[204:207], v[24:27]
	v_mfma_f32_16x16x32_bf16 v[20:23], v[148:151], v[212:215], v[20:23]
	v_mfma_f32_16x16x32_bf16 v[16:19], v[196:199], v[212:215], v[16:19]
	v_mfma_f32_16x16x32_bf16 v[12:15], v[148:151], v[220:223], v[12:15]
	v_mfma_f32_16x16x32_bf16 v[8:11], v[196:199], v[220:223], v[8:11]
	v_mfma_f32_16x16x32_bf16 v[4:7], v[148:151], v[228:231], v[4:7]
	v_mfma_f32_16x16x32_bf16 v[0:3], v[196:199], v[228:231], v[0:3]
	s_setprio 0
	s_barrier
	s_add_i32 s68, 0, 0x18000
	s_add_i32 s69, 0, 0x1c000
	v_add_u32_e32 v140, s68, v179
	v_add_u32_e32 v170, s69, v179
	ds_read_b128 v[120:123], v140
	ds_read_b128 v[124:127], v140 offset:1024
	ds_read_b128 v[136:139], v140 offset:2048
	ds_read_b128 v[140:143], v140 offset:3072
	ds_read_b128 v[144:147], v170
	ds_read_b128 v[148:151], v170 offset:1024
	ds_read_b128 v[192:195], v170 offset:2048
	ds_read_b128 v[196:199], v170 offset:3072
	s_add_u32 s52, s52, 0x40000
	s_addc_u32 s53, s53, 0
	s_mov_b32 m0, s59
	v_lshl_add_u64 v[184:185], s[52:53], 0, v[152:153]
	ds_read_b128 v[200:203], v191 offset:32768
	ds_read_b128 v[204:207], v191 offset:33792
	ds_read_b128 v[208:211], v191 offset:34816
	ds_read_b128 v[212:215], v191 offset:35840
	ds_read_b128 v[216:219], v191 offset:36864
	ds_read_b128 v[220:223], v191 offset:37888
	ds_read_b128 v[224:227], v191 offset:38912
	ds_read_b128 v[228:231], v191 offset:39936
	global_load_lds_dwordx4 v[184:185], off
	v_lshl_add_u64 v[184:185], s[52:53], 0, v[156:157]
	s_mov_b32 m0, s60
	s_nop 0
	global_load_lds_dwordx4 v[184:185], off
	s_waitcnt vmcnt(8)
	s_waitcnt lgkmcnt(0)
	s_barrier
	s_setprio 1
	s_waitcnt lgkmcnt(0)
	v_mfma_f32_16x16x32_bf16 v[132:135], v[120:123], v[200:203], v[132:135]
	v_mfma_f32_16x16x32_bf16 v[128:131], v[136:139], v[200:203], v[128:131]
	v_mfma_f32_16x16x32_bf16 v[116:119], v[120:123], v[208:211], v[116:119]
	v_mfma_f32_16x16x32_bf16 v[112:115], v[136:139], v[208:211], v[112:115]
	v_mfma_f32_16x16x32_bf16 v[108:111], v[120:123], v[216:219], v[108:111]
	v_mfma_f32_16x16x32_bf16 v[104:107], v[136:139], v[216:219], v[104:107]
	v_mfma_f32_16x16x32_bf16 v[100:103], v[120:123], v[224:227], v[100:103]
	v_mfma_f32_16x16x32_bf16 v[96:99], v[136:139], v[224:227], v[96:99]
	v_mfma_f32_16x16x32_bf16 v[132:135], v[124:127], v[204:207], v[132:135]
	v_mfma_f32_16x16x32_bf16 v[128:131], v[140:143], v[204:207], v[128:131]
	v_mfma_f32_16x16x32_bf16 v[116:119], v[124:127], v[212:215], v[116:119]
	v_mfma_f32_16x16x32_bf16 v[112:115], v[140:143], v[212:215], v[112:115]
	v_mfma_f32_16x16x32_bf16 v[108:111], v[124:127], v[220:223], v[108:111]
	v_mfma_f32_16x16x32_bf16 v[104:107], v[140:143], v[220:223], v[104:107]
	v_mfma_f32_16x16x32_bf16 v[100:103], v[124:127], v[228:231], v[100:103]
	v_mfma_f32_16x16x32_bf16 v[96:99], v[140:143], v[228:231], v[96:99]
	s_setprio 0
	s_setprio 1
	v_mfma_f32_16x16x32_bf16 v[60:63], v[144:147], v[200:203], v[60:63]
	v_mfma_f32_16x16x32_bf16 v[56:59], v[192:195], v[200:203], v[56:59]
	v_mfma_f32_16x16x32_bf16 v[52:55], v[144:147], v[208:211], v[52:55]
	v_mfma_f32_16x16x32_bf16 v[48:51], v[192:195], v[208:211], v[48:51]
	v_mfma_f32_16x16x32_bf16 v[44:47], v[144:147], v[216:219], v[44:47]
	v_mfma_f32_16x16x32_bf16 v[40:43], v[192:195], v[216:219], v[40:43]
	v_mfma_f32_16x16x32_bf16 v[36:39], v[144:147], v[224:227], v[36:39]
	v_mfma_f32_16x16x32_bf16 v[32:35], v[192:195], v[224:227], v[32:35]
	v_mfma_f32_16x16x32_bf16 v[60:63], v[148:151], v[204:207], v[60:63]
	v_mfma_f32_16x16x32_bf16 v[56:59], v[196:199], v[204:207], v[56:59]
	v_mfma_f32_16x16x32_bf16 v[52:55], v[148:151], v[212:215], v[52:55]
	v_mfma_f32_16x16x32_bf16 v[48:51], v[196:199], v[212:215], v[48:51]
	v_mfma_f32_16x16x32_bf16 v[44:47], v[148:151], v[220:223], v[44:47]
	v_mfma_f32_16x16x32_bf16 v[40:43], v[196:199], v[220:223], v[40:43]
	v_mfma_f32_16x16x32_bf16 v[36:39], v[148:151], v[228:231], v[36:39]
	v_mfma_f32_16x16x32_bf16 v[32:35], v[196:199], v[228:231], v[32:35]
	s_setprio 0
	s_barrier
; #define PG8_STAGE(bufoff, gbase, voff) do { _Pragma("unroll") for (int _i = 0; _i < 2; ++_i) \
;         __builtin_amdgcn_global_load_lds((const unsigned*)((const char*)(gbase) + (voff)[_i]), (PG8_LAS unsigned*)(lds + (bufoff) + ldsw + _i * 8192), 16, 0, 0); } while (0)
; #define PG8_LDA(dst, b, h) do { _Pragma("unroll") for (int m = 0; m < 4; ++m) _Pragma("unroll") for (int k = 0; k < 2; ++k) dst[m][k] = *(const PG8_LAS bf16x8*)(lds + PG8_SA(b, h) + aoff + m * 2048 + k * 1024); } while (0)
; #define PG8_MMA(ai, bj, At, Bt) do { __builtin_amdgcn_s_setprio(1); _Pragma("unroll") for (int m = 0; m < 4; ++m) _Pragma("unroll") for (int n = 0; n < 2; ++n) _Pragma("unroll") for (int k = 0; k < 2; ++k) \
;         acc[ai][bj][m][n] = __builtin_amdgcn_mfma_f32_16x16x32_bf16(Bt[n][k], At[m][k], acc[ai][bj][m][n], 0, 0, 0); __builtin_amdgcn_s_setprio(0); } while (0)
; #define PG8_WAIT_V(n) asm volatile("s_waitcnt vmcnt(" #n ")" ::: "memory")
; #define PG8_WAIT_L(n) asm volatile("s_waitcnt lgkmcnt(" #n ")" ::: "memory")
; #define PG8_BAR __builtin_amdgcn_s_barrier()
; #define PG8_SCHED __builtin_amdgcn_sched_barrier(0)
; template <class Epi, class Sched, bool ALIGN_EPI = false, bool SP2 = false>
; __device__ __forceinline__ void gemm_phase(PG8_LAS unsigned char* lds, const Gemm g, const Sched& S, const Epi& E) {
;     ...
;         for (int t = 0; t < nt; t += 2) {
;     ...
;             PG8_LDA(At, 1, 1); PG8_STAGE(PG8_SB(1, 0), b3, voffB); PG8_STAGE(PG8_SB(1, 1), b3 + hstepB, voffB); PG8_STAGE(PG8_SA(1, 0), a3, voffA);
;             PG8_WAIT_V(8); PG8_WAIT_L(0); PG8_BAR; PG8_MMA(1, 0, At, B0); PG8_MMA(1, 1, At, B1); PG8_BAR; PG8_SCHED;
	s_add_i32 s52, s68, s57
	v_lshl_add_u64 v[168:169], v[168:169], 0, s[30:31]
	s_mov_b32 m0, s52
	ds_read_b128 v[200:203], v191 offset:49152
	ds_read_b128 v[204:207], v191 offset:50176
	ds_read_b128 v[208:211], v191 offset:51200
	ds_read_b128 v[212:215], v191 offset:52224
	ds_read_b128 v[216:219], v191 offset:53248
	ds_read_b128 v[220:223], v191 offset:54272
	ds_read_b128 v[224:227], v191 offset:55296
	ds_read_b128 v[228:231], v191 offset:56320
	global_load_lds_dwordx4 v[168:169], off
	s_add_i32 m0, s52, 0x2000
	s_add_u32 s36, s36, 0x40080
	v_lshl_add_u64 v[168:169], v[172:173], 0, s[30:31]
	s_addc_u32 s37, s37, 0
	s_add_i32 s52, s69, s57
	global_load_lds_dwordx4 v[168:169], off
	v_lshl_add_u64 v[168:169], s[36:37], 0, v[154:155]
	s_mov_b32 m0, s52
	s_nop 0
	global_load_lds_dwordx4 v[168:169], off
	v_lshl_add_u64 v[168:169], s[36:37], 0, v[158:159]
	s_add_i32 m0, s52, 0x2000
	s_nop 0
	global_load_lds_dwordx4 v[168:169], off
	v_lshl_add_u64 v[168:169], v[176:177], 0, s[30:31]
	s_mov_b32 m0, s17
	s_nop 0
	global_load_lds_dwordx4 v[168:169], off
	v_lshl_add_u64 v[168:169], v[180:181], 0, s[30:31]
	s_mov_b32 m0, s62
	s_nop 0
	global_load_lds_dwordx4 v[168:169], off
	s_waitcnt vmcnt(8)
	s_waitcnt lgkmcnt(0)
	s_barrier
	s_setprio 1
	s_waitcnt lgkmcnt(0)
	v_mfma_f32_16x16x32_bf16 v[92:95], v[120:123], v[200:203], v[92:95]
	v_mfma_f32_16x16x32_bf16 v[88:91], v[136:139], v[200:203], v[88:91]
	v_mfma_f32_16x16x32_bf16 v[84:87], v[120:123], v[208:211], v[84:87]
	v_mfma_f32_16x16x32_bf16 v[80:83], v[136:139], v[208:211], v[80:83]
	v_mfma_f32_16x16x32_bf16 v[76:79], v[120:123], v[216:219], v[76:79]
	v_mfma_f32_16x16x32_bf16 v[72:75], v[136:139], v[216:219], v[72:75]
	v_mfma_f32_16x16x32_bf16 v[68:71], v[120:123], v[224:227], v[68:71]
	v_mfma_f32_16x16x32_bf16 v[64:67], v[136:139], v[224:227], v[64:67]
	v_mfma_f32_16x16x32_bf16 v[92:95], v[124:127], v[204:207], v[92:95]
	v_mfma_f32_16x16x32_bf16 v[88:91], v[140:143], v[204:207], v[88:91]
	v_mfma_f32_16x16x32_bf16 v[84:87], v[124:127], v[212:215], v[84:87]
	v_mfma_f32_16x16x32_bf16 v[80:83], v[140:143], v[212:215], v[80:83]
	v_mfma_f32_16x16x32_bf16 v[76:79], v[124:127], v[220:223], v[76:79]
	v_mfma_f32_16x16x32_bf16 v[72:75], v[140:143], v[220:223], v[72:75]
	v_mfma_f32_16x16x32_bf16 v[68:71], v[124:127], v[228:231], v[68:71]
	v_mfma_f32_16x16x32_bf16 v[64:67], v[140:143], v[228:231], v[64:67]
	s_setprio 0
	s_setprio 1
	v_mfma_f32_16x16x32_bf16 v[28:31], v[144:147], v[200:203], v[28:31]
	v_mfma_f32_16x16x32_bf16 v[24:27], v[192:195], v[200:203], v[24:27]
	v_mfma_f32_16x16x32_bf16 v[20:23], v[144:147], v[208:211], v[20:23]
	v_mfma_f32_16x16x32_bf16 v[16:19], v[192:195], v[208:211], v[16:19]
	v_mfma_f32_16x16x32_bf16 v[12:15], v[144:147], v[216:219], v[12:15]
	v_mfma_f32_16x16x32_bf16 v[8:11], v[192:195], v[216:219], v[8:11]
	v_mfma_f32_16x16x32_bf16 v[4:7], v[144:147], v[224:227], v[4:7]
	v_mfma_f32_16x16x32_bf16 v[0:3], v[192:195], v[224:227], v[0:3]
	v_mfma_f32_16x16x32_bf16 v[28:31], v[148:151], v[204:207], v[28:31]
	v_mfma_f32_16x16x32_bf16 v[24:27], v[196:199], v[204:207], v[24:27]
	v_mfma_f32_16x16x32_bf16 v[20:23], v[148:151], v[212:215], v[20:23]
	v_mfma_f32_16x16x32_bf16 v[16:19], v[196:199], v[212:215], v[16:19]
	v_mfma_f32_16x16x32_bf16 v[12:15], v[148:151], v[220:223], v[12:15]
	v_mfma_f32_16x16x32_bf16 v[8:11], v[196:199], v[220:223], v[8:11]
	v_mfma_f32_16x16x32_bf16 v[4:7], v[148:151], v[228:231], v[4:7]
	v_mfma_f32_16x16x32_bf16 v[0:3], v[196:199], v[228:231], v[0:3]
	s_setprio 0
	s_barrier
	s_add_u32 s12, s12, 0x100
	s_addc_u32 s13, s13, 0
	s_add_u32 s45, s45, 0x100
	s_addc_u32 s47, s47, 0
	s_cmp_ge_i32 s67, s14
	s_mov_b32 s36, s67
	s_cbranch_scc0 .LBB0_1695

; __device__ __forceinline__ void load_row_stats(const float* sp, int row0, RowStats& r) {
;     ...
;         for (int m = 0; m < 4; ++m) { const float* p = sp + (size_t)(row0 + ai * HALF + m * 16) * 8; const f32x4 a = *(const f32x4*)p, b = *(const f32x4*)(p + 4);
;             const float s1 = (a[0] + a[2]) + (b[0] + b[2]), s2 = (a[1] + a[3]) + (b[1] + b[3]); const float mu = s1 * (1.f / 1024.f); const float var = s2 * (1.f / 1024.f) - mu * mu;
;             r.mu[ai][m] = mu; r.rs[ai][m] = __builtin_amdgcn_rsqf(__builtin_fmaxf(var, 0.f) + 1e-5f); } }
.LBB0_1698:
	s_lshl_b32 s10, s10, 8
	v_mov_b32_e32 v120, v171
	v_mov_b32_e32 v121, v175
	s_add_i32 s10, s10, s15
	s_cmp_lt_u32 s18, 4
	v_add_u32_e32 v222, s10, v120
	v_ashrrev_i32_e32 v223, 31, v222
	s_cselect_b32 s99, 1, 0
	v_readfirstlane_b32 s98, v254
	v_and_b32_e32 v124, 0xffffff00, v222
	s_nop 0
	s_cmpk_lt_u32 s98, 0x100
	s_cbranch_scc0 .Lrs5_skip
	v_pk_add_f32 v[124:125], v[246:247], v[248:249]
	v_pk_add_f32 v[136:137], v[250:251], v[252:253]
	s_nop 0
	v_pk_add_f32 v[124:125], v[136:137], v[124:125]
	s_nop 0
	v_pk_mul_f32 v[124:125], v[124:125], s[42:43] op_sel_hi:[1,0]
	v_lshlrev_b32_e32 v126, 3, v254
	v_add_u32_e32 v126, 0x22400, v126
	ds_write_b64 v126, v[124:125]

; __device__ __forceinline__ void load_row_stats(const float* sp, int row0, RowStats& r) {
;     ...
;         for (int m = 0; m < 4; ++m) { const float* p = sp + (size_t)(row0 + ai * HALF + m * 16) * 8; const f32x4 a = *(const f32x4*)p, b = *(const f32x4*)(p + 4);
;             const float s1 = (a[0] + a[2]) + (b[0] + b[2]), s2 = (a[1] + a[3]) + (b[1] + b[3]); const float mu = s1 * (1.f / 1024.f); const float var = s2 * (1.f / 1024.f) - mu * mu;
;             r.mu[ai][m] = mu; r.rs[ai][m] = __builtin_amdgcn_rsqf(__builtin_fmaxf(var, 0.f) + 1e-5f); } }
.LBB0_1995:
	s_lshl_b32 s35, s44, 8
	v_mov_b32_e32 v112, v179
	v_mov_b32_e32 v113, v185
	s_add_i32 s35, s35, s54
	s_andn2_b64 vcc, exec, s[38:39]
	v_add_u32_e32 v192, s35, v112
	v_ashrrev_i32_e32 v193, 31, v192
	s_cselect_b32 s99, 1, 0
	v_readfirstlane_b32 s98, v254
	v_and_b32_e32 v114, 0xffffff00, v192
	s_nop 0
	s_cmpk_lt_u32 s98, 0x100
	s_cbranch_scc0 .Lrs9_skip
	v_pk_add_f32 v[114:115], v[246:247], v[248:249]
	v_pk_add_f32 v[118:119], v[250:251], v[252:253]
	s_nop 0
	v_pk_add_f32 v[114:115], v[118:119], v[114:115]
	s_nop 0
	v_pk_mul_f32 v[114:115], v[114:115], s[30:31] op_sel_hi:[1,0]
	v_lshlrev_b32_e32 v116, 3, v254
	v_add_u32_e32 v116, 0x22400, v116
	ds_write_b64 v116, v[114:115]
